# y = yq + sa*sc0 + v*sc1 moved from the recurrence waves (per step) to the helper POST (per chunk); recurrence writes yq and sa
# speedup vs baseline: 1.0053x; 1.0034x over previous
.LBB0_533:
	s_and_b64 vcc, exec, s[0:1]
	s_cbranch_vccz .LBB0_508
	v_mov_b32_e32 v57, v241
	s_ashr_i32 s48, s8, 5
	s_bfe_u32 s9, s8, 0x40001
	v_readfirstlane_b32 s0, v57
	s_and_b32 s10, s8, 1
	s_ashr_i32 s11, s0, 6
	s_ashr_i32 s49, s48, 31
	s_cmp_gt_i32 s11, 3
	s_mov_b64 s[0:1], -1
	s_cbranch_scc0 .LBB0_606
	s_waitcnt vmcnt(0)
	v_add_u32_e32 v198, 0xffffff00, v241
	v_lshrrev_b32_e32 v206, 3, v198
	v_and_b32_e32 v207, 7, v198
	s_lshl_b32 s0, s9, 6
	v_lshl_add_u32 v208, v207, 2, s0
	v_cmp_eq_u32_e64 s[38:39], 0, v207
	v_cmp_gt_u32_e64 s[28:29], 16, v206
	s_cmp_eq_u32 s10, 0
	s_cselect_b64 s[40:41], -1, 0
	s_nop 3
	s_and_b64 s[40:41], s[40:41], s[38:39]
	v_lshlrev_b32_e32 v199, 2, v208
	v_readlane_b32 s4, v255, 32
	v_readlane_b32 s5, v255, 33
	v_readlane_b32 s12, v255, 47
	v_readlane_b32 s13, v255, 48
	v_readlane_b32 s0, v255, 49
	v_readlane_b32 s1, v255, 50
	s_nop 4
	s_add_u32 s6, s4, 0x1000
	s_addc_u32 s7, s5, 0
	global_load_dwordx4 v[0:3], v199, s[4:5]
	global_load_dwordx4 v[4:7], v199, s[4:5] offset:128
	global_load_dwordx4 v[8:11], v199, s[6:7]
	global_load_dwordx4 v[12:15], v199, s[6:7] offset:128
	s_add_u32 s6, s4, 0x2000
	s_addc_u32 s7, s5, 0
	global_load_dwordx4 v[24:27], v199, s[12:13]
	global_load_dwordx4 v[28:31], v199, s[12:13] offset:128
	global_load_dwordx4 v[16:19], v199, s[6:7]
	global_load_dwordx4 v[20:23], v199, s[6:7] offset:128
	global_load_dwordx4 v[32:35], v199, s[0:1]
	global_load_dwordx4 v[36:39], v199, s[0:1] offset:128
	global_load_dwordx4 v[40:43], v199, s[64:65]
	global_load_dwordx4 v[44:47], v199, s[64:65] offset:128
	v_mov_b32_e32 v48, 0x3fb8aa3b
	v_mov_b32_e32 v49, 0x3fb8aa3b
	s_mul_i32 s0, s48, 0x810
	v_add_u32_e32 v209, s0, v206
	v_mov_b32_e32 v211, 0
	v_lshlrev_b32_e32 v210, 1, v208
	s_movk_i32 s14, 0x1a00
	v_mad_u64_u32 v[182:183], s[0:1], v209, s14, v[210:211]
	s_add_u32 s4, s86, 0x81a7000
	s_addc_u32 s5, s87, 0
	v_lshl_add_u64 v[182:183], v[182:183], 0, s[4:5]
	s_mov_b64 s[0:1], 0x1000
	v_lshl_add_u64 v[178:179], v[182:183], 0, s[0:1]
	v_lshl_add_u64 v[180:181], v[178:179], 0, s[0:1]
	v_lshl_add_u32 v198, v209, 11, v210
	v_mov_b32_e32 v210, v198
	s_add_u32 s4, s86, 0xeb48000
	s_addc_u32 s5, s87, 0
	v_lshl_add_u64 v[186:187], v[210:211], 0, s[4:5]
	s_add_u32 s4, s86, 0x10bc8000
	s_addc_u32 s5, s87, 0
	v_lshl_add_u64 v[188:189], v[210:211], 0, s[4:5]
	s_lshl_b32 s0, s9, 6
	s_lshl_b32 s1, s10, 5
	s_add_i32 s0, s0, s1
	v_lshl_add_u32 v198, v207, 2, s0
	v_lshlrev_b32_e32 v198, 1, v198
	v_lshl_add_u32 v210, v209, 11, v198
	s_add_u32 s4, s86, 0x5700000
	s_addc_u32 s5, s87, 0
	v_lshl_add_u64 v[190:191], v[210:211], 0, s[4:5]
	s_lshl_b32 s0, s9, 2
	v_lshl_add_u32 v210, v209, 6, s0
	s_add_u32 s4, s86, 0x7884000
	s_addc_u32 s5, s87, 0
	v_lshl_add_u64 v[192:193], v[210:211], 0, s[4:5]
	v_mul_u32_u24_e32 v194, 0x600, v206
	v_lshl_add_u32 v194, v207, 4, v194
	s_lshl_b32 s0, s10, 7
	v_mul_u32_u24_e32 v222, 0x600, v206
	v_lshl_add_u32 v222, v207, 4, v222
	v_add_u32_e32 v222, s0, v222
	v_lshlrev_b32_e32 v195, 7, v206
	v_lshl_add_u32 v195, v207, 4, v195
	v_add_u32_e32 v195, 0x18000, v195
	v_lshlrev_b32_e32 v196, 2, v206
	v_add_u32_e32 v196, 0x1a000, v196
	v_lshlrev_b32_e32 v197, 3, v206
	v_add_u32_e32 v197, 0x1a100, v197
	global_load_dwordx2 v[52:53], v[178:179], off
	global_load_dwordx2 v[54:55], v[178:179], off offset:64
	global_load_dwordx2 v[56:57], v[178:179], off offset:2048
	global_load_dwordx2 v[58:59], v[178:179], off offset:2112
	global_load_dwordx2 v[60:61], v[180:181], off
	global_load_dwordx2 v[62:63], v[180:181], off offset:64
	global_load_dwordx2 v[64:65], v[182:183], off offset:-2560
	global_load_dwordx2 v[66:67], v[182:183], off offset:-2496
	global_load_dwordx2 v[68:69], v[182:183], off offset:-512
	global_load_dwordx2 v[70:71], v[182:183], off offset:-448
	global_load_dwordx2 v[72:73], v[178:179], off offset:-2560
	global_load_dwordx2 v[74:75], v[178:179], off offset:-2496
	global_load_dwordx2 v[76:77], v[186:187], off
	global_load_dwordx2 v[78:79], v[186:187], off offset:64
	global_load_dwordx2 v[80:81], v[188:189], off
	global_load_dwordx2 v[82:83], v[188:189], off offset:64
	s_mov_b32 s13, 0
	s_waitcnt vmcnt(0)
	v_cmp_ne_u32_e64 s[6:7], 0, v206
	s_nop 3
	v_cndmask_b32_e64 v64, 0, v64, s[6:7]
	v_cndmask_b32_e64 v65, 0, v65, s[6:7]
	v_cndmask_b32_e64 v66, 0, v66, s[6:7]
	v_cndmask_b32_e64 v67, 0, v67, s[6:7]
	v_cndmask_b32_e64 v68, 0, v68, s[6:7]
	v_cndmask_b32_e64 v69, 0, v69, s[6:7]
	v_cndmask_b32_e64 v70, 0, v70, s[6:7]
	v_cndmask_b32_e64 v71, 0, v71, s[6:7]
	v_cndmask_b32_e64 v72, 0, v72, s[6:7]
	v_cndmask_b32_e64 v73, 0, v73, s[6:7]
	v_cndmask_b32_e64 v74, 0, v74, s[6:7]
	v_cndmask_b32_e64 v75, 0, v75, s[6:7]
	v_lshlrev_b32_e32 v84, 16, v52
	v_and_b32_e32 v85, 0xffff0000, v52
	v_lshlrev_b32_e32 v86, 16, v53
	v_and_b32_e32 v87, 0xffff0000, v53
	v_lshlrev_b32_e32 v88, 16, v54
	v_and_b32_e32 v89, 0xffff0000, v54
	v_lshlrev_b32_e32 v90, 16, v55
	v_and_b32_e32 v91, 0xffff0000, v55
	v_lshlrev_b32_e32 v124, 16, v64
	v_and_b32_e32 v125, 0xffff0000, v64
	v_lshlrev_b32_e32 v126, 16, v65
	v_and_b32_e32 v127, 0xffff0000, v65
	v_lshlrev_b32_e32 v128, 16, v66
	v_and_b32_e32 v129, 0xffff0000, v66
	v_lshlrev_b32_e32 v130, 16, v67
	v_and_b32_e32 v131, 0xffff0000, v67
	v_pk_add_f32 v[124:125], v[124:125], v[84:85] neg_lo:[0,1] neg_hi:[0,1]
	v_pk_add_f32 v[126:127], v[126:127], v[86:87] neg_lo:[0,1] neg_hi:[0,1]
	v_pk_add_f32 v[128:129], v[128:129], v[88:89] neg_lo:[0,1] neg_hi:[0,1]
	v_pk_add_f32 v[130:131], v[130:131], v[90:91] neg_lo:[0,1] neg_hi:[0,1]
	v_pk_fma_f32 v[84:85], v[0:1], v[124:125], v[84:85]
	v_pk_fma_f32 v[86:87], v[2:3], v[126:127], v[86:87]
	v_pk_fma_f32 v[88:89], v[4:5], v[128:129], v[88:89]
	v_pk_fma_f32 v[90:91], v[6:7], v[130:131], v[90:91]
	v_lshlrev_b32_e32 v92, 16, v56
	v_and_b32_e32 v93, 0xffff0000, v56
	v_lshlrev_b32_e32 v94, 16, v57
	v_and_b32_e32 v95, 0xffff0000, v57
	v_lshlrev_b32_e32 v96, 16, v58
	v_and_b32_e32 v97, 0xffff0000, v58
	v_lshlrev_b32_e32 v98, 16, v59
	v_and_b32_e32 v99, 0xffff0000, v59
	v_lshlrev_b32_e32 v124, 16, v68
	v_and_b32_e32 v125, 0xffff0000, v68
	v_lshlrev_b32_e32 v126, 16, v69
	v_and_b32_e32 v127, 0xffff0000, v69
	v_lshlrev_b32_e32 v128, 16, v70
	v_and_b32_e32 v129, 0xffff0000, v70
	v_lshlrev_b32_e32 v130, 16, v71
	v_and_b32_e32 v131, 0xffff0000, v71
	v_pk_add_f32 v[124:125], v[124:125], v[92:93] neg_lo:[0,1] neg_hi:[0,1]
	v_pk_add_f32 v[126:127], v[126:127], v[94:95] neg_lo:[0,1] neg_hi:[0,1]
	v_pk_add_f32 v[128:129], v[128:129], v[96:97] neg_lo:[0,1] neg_hi:[0,1]
	v_pk_add_f32 v[130:131], v[130:131], v[98:99] neg_lo:[0,1] neg_hi:[0,1]
	v_pk_fma_f32 v[92:93], v[8:9], v[124:125], v[92:93]
	v_pk_fma_f32 v[94:95], v[10:11], v[126:127], v[94:95]
	v_pk_fma_f32 v[96:97], v[12:13], v[128:129], v[96:97]
	v_pk_fma_f32 v[98:99], v[14:15], v[130:131], v[98:99]
	v_lshlrev_b32_e32 v100, 16, v60
	v_and_b32_e32 v101, 0xffff0000, v60
	v_lshlrev_b32_e32 v102, 16, v61
	v_and_b32_e32 v103, 0xffff0000, v61
	v_lshlrev_b32_e32 v104, 16, v62
	v_and_b32_e32 v105, 0xffff0000, v62
	v_lshlrev_b32_e32 v106, 16, v63
	v_and_b32_e32 v107, 0xffff0000, v63
	v_lshlrev_b32_e32 v124, 16, v72
	v_and_b32_e32 v125, 0xffff0000, v72
	v_lshlrev_b32_e32 v126, 16, v73
	v_and_b32_e32 v127, 0xffff0000, v73
	v_lshlrev_b32_e32 v128, 16, v74
	v_and_b32_e32 v129, 0xffff0000, v74
	v_lshlrev_b32_e32 v130, 16, v75
	v_and_b32_e32 v131, 0xffff0000, v75
	v_pk_add_f32 v[124:125], v[124:125], v[100:101] neg_lo:[0,1] neg_hi:[0,1]
	v_pk_add_f32 v[126:127], v[126:127], v[102:103] neg_lo:[0,1] neg_hi:[0,1]
	v_pk_add_f32 v[128:129], v[128:129], v[104:105] neg_lo:[0,1] neg_hi:[0,1]
	v_pk_add_f32 v[130:131], v[130:131], v[106:107] neg_lo:[0,1] neg_hi:[0,1]
	v_pk_fma_f32 v[100:101], v[16:17], v[124:125], v[100:101]
	v_pk_fma_f32 v[102:103], v[18:19], v[126:127], v[102:103]
	v_pk_fma_f32 v[104:105], v[20:21], v[128:129], v[104:105]
	v_pk_fma_f32 v[106:107], v[22:23], v[130:131], v[106:107]
	v_lshlrev_b32_e32 v108, 16, v80
	v_and_b32_e32 v109, 0xffff0000, v80
	v_lshlrev_b32_e32 v110, 16, v81
	v_and_b32_e32 v111, 0xffff0000, v81
	v_lshlrev_b32_e32 v112, 16, v82
	v_and_b32_e32 v113, 0xffff0000, v82
	v_lshlrev_b32_e32 v114, 16, v83
	v_and_b32_e32 v115, 0xffff0000, v83
	v_lshlrev_b32_e32 v116, 16, v76
	v_and_b32_e32 v117, 0xffff0000, v76
	v_lshlrev_b32_e32 v118, 16, v77
	v_and_b32_e32 v119, 0xffff0000, v77
	v_lshlrev_b32_e32 v120, 16, v78
	v_and_b32_e32 v121, 0xffff0000, v78
	v_lshlrev_b32_e32 v122, 16, v79
	v_and_b32_e32 v123, 0xffff0000, v79
	v_pk_mul_f32 v[132:133], v[92:93], v[24:25]
	v_pk_mul_f32 v[134:135], v[94:95], v[26:27]
	v_pk_mul_f32 v[136:137], v[96:97], v[28:29]
	v_pk_mul_f32 v[138:139], v[98:99], v[30:31]
	v_pk_add_f32 v[124:125], v[108:109], -1.0 op_sel_hi:[1,0]
	v_pk_add_f32 v[126:127], v[110:111], -1.0 op_sel_hi:[1,0]
	v_pk_add_f32 v[128:129], v[112:113], -1.0 op_sel_hi:[1,0]
	v_pk_add_f32 v[130:131], v[114:115], -1.0 op_sel_hi:[1,0]
	v_pk_fma_f32 v[124:125], v[32:33], v[124:125], 1.0 op_sel_hi:[1,1,0]
	v_pk_fma_f32 v[126:127], v[34:35], v[126:127], 1.0 op_sel_hi:[1,1,0]
	v_pk_fma_f32 v[128:129], v[36:37], v[128:129], 1.0 op_sel_hi:[1,1,0]
	v_pk_fma_f32 v[130:131], v[38:39], v[130:131], 1.0 op_sel_hi:[1,1,0]
	v_pk_mul_f32 v[140:141], v[124:125], v[92:93]
	v_pk_mul_f32 v[142:143], v[126:127], v[94:95]
	v_pk_mul_f32 v[144:145], v[128:129], v[96:97]
	v_pk_mul_f32 v[146:147], v[130:131], v[98:99]
	v_pk_mul_f32 v[148:149], v[84:85], v[140:141]
	v_pk_mul_f32 v[150:151], v[86:87], v[142:143]
	v_pk_mul_f32 v[152:153], v[88:89], v[144:145]
	v_pk_mul_f32 v[154:155], v[90:91], v[146:147]
	v_pk_mul_f32 v[156:157], v[132:133], v[108:109]
	v_pk_mul_f32 v[158:159], v[134:135], v[110:111]
	v_pk_mul_f32 v[160:161], v[136:137], v[112:113]
	v_pk_mul_f32 v[162:163], v[138:139], v[114:115]
	v_pk_mul_f32 v[124:125], v[148:149], v[40:41]
	v_pk_mul_f32 v[126:127], v[150:151], v[42:43]
	v_pk_mul_f32 v[128:129], v[152:153], v[44:45]
	v_pk_mul_f32 v[130:131], v[154:155], v[46:47]
	v_pk_add_f32 v[124:125], v[124:125], v[126:127]
	v_pk_add_f32 v[128:129], v[128:129], v[130:131]
	v_pk_add_f32 v[124:125], v[124:125], v[128:129]
	v_add_f32_e32 v173, v124, v125
	v_pk_mul_f32 v[124:125], v[156:157], v[84:85]
	v_pk_mul_f32 v[126:127], v[158:159], v[86:87]
	v_pk_mul_f32 v[128:129], v[160:161], v[88:89]
	v_pk_mul_f32 v[130:131], v[162:163], v[90:91]
	v_pk_add_f32 v[124:125], v[124:125], v[126:127]
	v_pk_add_f32 v[128:129], v[128:129], v[130:131]
	v_pk_add_f32 v[124:125], v[124:125], v[128:129]
	v_add_f32_e32 v174, v124, v125
	v_pk_mul_f32 v[124:125], v[132:133], v[132:133]
	v_pk_mul_f32 v[126:127], v[134:135], v[134:135]
	v_pk_mul_f32 v[128:129], v[136:137], v[136:137]
	v_pk_mul_f32 v[130:131], v[138:139], v[138:139]
	v_pk_add_f32 v[124:125], v[124:125], v[126:127]
	v_pk_add_f32 v[128:129], v[128:129], v[130:131]
	v_pk_add_f32 v[124:125], v[124:125], v[128:129]
	v_add_f32_e32 v172, v124, v125
	v_pk_add_f32 v[148:149], v[148:149], v[150:151]
	v_pk_add_f32 v[152:153], v[152:153], v[154:155]
	v_pk_add_f32 v[148:149], v[148:149], v[152:153]
	v_add_f32_e32 v175, v148, v149
	v_pk_mul_f32 v[116:117], v[116:117], v[48:49]
	v_pk_mul_f32 v[118:119], v[118:119], v[48:49]
	v_pk_mul_f32 v[120:121], v[120:121], v[48:49]
	v_pk_mul_f32 v[122:123], v[122:123], v[48:49]
	v_add_f32_dpp v172, v172, v172 quad_perm:[1,0,3,2] row_mask:0xf bank_mask:0xf bound_ctrl:1
	v_add_f32_dpp v173, v173, v173 quad_perm:[1,0,3,2] row_mask:0xf bank_mask:0xf bound_ctrl:1
	v_add_f32_dpp v174, v174, v174 quad_perm:[1,0,3,2] row_mask:0xf bank_mask:0xf bound_ctrl:1
	v_add_f32_dpp v175, v175, v175 quad_perm:[1,0,3,2] row_mask:0xf bank_mask:0xf bound_ctrl:1
	v_add_f32_dpp v172, v172, v172 quad_perm:[2,3,0,1] row_mask:0xf bank_mask:0xf bound_ctrl:1
	v_add_f32_dpp v173, v173, v173 quad_perm:[2,3,0,1] row_mask:0xf bank_mask:0xf bound_ctrl:1
	v_add_f32_dpp v174, v174, v174 quad_perm:[2,3,0,1] row_mask:0xf bank_mask:0xf bound_ctrl:1
	v_add_f32_dpp v175, v175, v175 quad_perm:[2,3,0,1] row_mask:0xf bank_mask:0xf bound_ctrl:1
	v_add_f32_dpp v172, v172, v172 row_half_mirror row_mask:0xf bank_mask:0xf bound_ctrl:1
	v_add_f32_dpp v173, v173, v173 row_half_mirror row_mask:0xf bank_mask:0xf bound_ctrl:1
	v_add_f32_dpp v174, v174, v174 row_half_mirror row_mask:0xf bank_mask:0xf bound_ctrl:1
	v_add_f32_dpp v175, v175, v175 row_half_mirror row_mask:0xf bank_mask:0xf bound_ctrl:1
	v_exp_f32_e32 v116, v116
	v_exp_f32_e32 v117, v117
	v_exp_f32_e32 v118, v118
	v_exp_f32_e32 v119, v119
	v_exp_f32_e32 v120, v120
	v_exp_f32_e32 v121, v121
	v_exp_f32_e32 v122, v122
	v_exp_f32_e32 v123, v123
	v_rsq_f32_e32 v176, v172
	v_pk_mul_f32 v[148:149], v[116:117], v[84:85]
	v_pk_mul_f32 v[150:151], v[118:119], v[86:87]
	v_pk_mul_f32 v[152:153], v[120:121], v[88:89]
	v_pk_mul_f32 v[154:155], v[122:123], v[90:91]
	v_min_f32_e32 v176, 0x5368d4a5, v176
	v_mul_f32_e32 v174, v174, v176
	v_pk_mul_f32 v[164:165], v[132:133], v[176:177] op_sel_hi:[1,0] neg_lo:[1,0] neg_hi:[1,0]
	v_pk_mul_f32 v[166:167], v[134:135], v[176:177] op_sel_hi:[1,0] neg_lo:[1,0] neg_hi:[1,0]
	v_pk_mul_f32 v[168:169], v[136:137], v[176:177] op_sel_hi:[1,0] neg_lo:[1,0] neg_hi:[1,0]
	v_pk_mul_f32 v[170:171], v[138:139], v[176:177] op_sel_hi:[1,0] neg_lo:[1,0] neg_hi:[1,0]
	v_pk_mul_f32 v[156:157], v[156:157], v[176:177] op_sel_hi:[1,0]
	v_pk_mul_f32 v[158:159], v[158:159], v[176:177] op_sel_hi:[1,0]
	v_pk_mul_f32 v[160:161], v[160:161], v[176:177] op_sel_hi:[1,0]
	v_pk_mul_f32 v[162:163], v[162:163], v[176:177] op_sel_hi:[1,0]
	s_mul_i32 s14, s13, 0xc000
	v_add_u32_e32 v198, s14, v194
	ds_write_b128 v198, v[148:151] offset:0
	ds_write_b128 v198, v[152:155] offset:128
	ds_write_b128 v198, v[116:119] offset:256
	ds_write_b128 v198, v[120:123] offset:384
	ds_write_b128 v198, v[140:143] offset:512
	ds_write_b128 v198, v[144:147] offset:640
	ds_write_b128 v198, v[164:167] offset:768
	ds_write_b128 v198, v[168:171] offset:896
	ds_write_b128 v198, v[156:159] offset:1024
	ds_write_b128 v198, v[160:163] offset:1152
	ds_write_b128 v198, v[100:103] offset:1280
	ds_write_b128 v198, v[104:107] offset:1408
	s_lshl_b32 s14, s13, 7
	v_add_u32_e32 v199, s14, v196
	s_lshl_b32 s14, s13, 8
	v_add_u32_e32 v198, s14, v197
	ds_write_b32 v199, v173
	ds_write_b64 v198, v[174:175]
	s_mov_b64 s[0:1], 0x34000
	v_lshl_add_u64 v[178:179], v[178:179], 0, s[0:1]
	v_lshl_add_u64 v[180:181], v[180:181], 0, s[0:1]
	v_lshl_add_u64 v[182:183], v[182:183], 0, s[0:1]
	s_mov_b64 s[0:1], 0x10000
	v_lshl_add_u64 v[186:187], v[186:187], 0, s[0:1]
	v_lshl_add_u64 v[188:189], v[188:189], 0, s[0:1]
	global_load_dwordx2 v[52:53], v[178:179], off
	global_load_dwordx2 v[54:55], v[178:179], off offset:64
	global_load_dwordx2 v[56:57], v[178:179], off offset:2048
	global_load_dwordx2 v[58:59], v[178:179], off offset:2112
	global_load_dwordx2 v[60:61], v[180:181], off
	global_load_dwordx2 v[62:63], v[180:181], off offset:64
	global_load_dwordx2 v[64:65], v[182:183], off offset:-2560
	global_load_dwordx2 v[66:67], v[182:183], off offset:-2496
	global_load_dwordx2 v[68:69], v[182:183], off offset:-512
	global_load_dwordx2 v[70:71], v[182:183], off offset:-448
	global_load_dwordx2 v[72:73], v[178:179], off offset:-2560
	global_load_dwordx2 v[74:75], v[178:179], off offset:-2496
	global_load_dwordx2 v[76:77], v[186:187], off
	global_load_dwordx2 v[78:79], v[186:187], off offset:64
	global_load_dwordx2 v[80:81], v[188:189], off
	global_load_dwordx2 v[82:83], v[188:189], off offset:64
	s_waitcnt lgkmcnt(0)
	s_barrier
	s_mov_b32 s12, 0
.Lh_loop:
	s_cmp_eq_u32 s12, 0
	s_cbranch_scc1 .Lh_nopost
	s_add_i32 s13, s12, 1
	s_and_b32 s13, s13, 1
	s_lshl_b32 s14, s13, 12
	v_add_u32_e32 v198, s14, v195
	s_lshl_b32 s14, s13, 7
	v_add_u32_e32 v199, s14, v196
	ds_read_b128 v[200:203], v198
	ds_read_b128 v[212:215], v198 offset:12288
	s_lshl_b32 s14, s13, 8
	v_add_u32_e32 v198, s14, v197
	ds_read_b64 v[220:221], v198
	s_mul_i32 s14, s13, 0xc000
	v_add_u32_e32 v198, s14, v222
	ds_read_b128 v[216:219], v198 offset:1280
	ds_read_b32 v204, v199
	s_waitcnt lgkmcnt(0)
	v_fmac_f32_e32 v200, v212, v220
	v_fmac_f32_e32 v201, v213, v220
	v_fmac_f32_e32 v202, v214, v220
	v_fmac_f32_e32 v203, v215, v220
	v_fmac_f32_e32 v200, v216, v221
	v_fmac_f32_e32 v201, v217, v221
	v_fmac_f32_e32 v202, v218, v221
	v_fmac_f32_e32 v203, v219, v221
	v_cvt_pk_bf16_f32 v200, v200, v201
	v_cvt_pk_bf16_f32 v201, v202, v203
	global_store_dwordx2 v[190:191], v[200:201], off
	s_mov_b64 s[4:5], exec
	s_and_b64 exec, exec, s[40:41]
	s_cbranch_execz .Lh_nobeta_loop
	global_store_dword v[192:193], v204, off

.Lh_nobuild:
	s_waitcnt lgkmcnt(0)
	s_barrier
	s_add_i32 s12, s12, 1
	s_cmp_lt_u32 s12, 0x41
	s_cbranch_scc1 .Lh_loop
	s_mov_b32 s13, 0
	s_and_saveexec_b64 s[6:7], s[28:29]
	s_cbranch_execz .Lh_post_skip_last
	s_lshl_b32 s14, s13, 12
	v_add_u32_e32 v198, s14, v195
	s_lshl_b32 s14, s13, 7
	v_add_u32_e32 v199, s14, v196
	ds_read_b128 v[200:203], v198
	ds_read_b128 v[212:215], v198 offset:12288
	s_lshl_b32 s14, s13, 8
	v_add_u32_e32 v198, s14, v197
	ds_read_b64 v[220:221], v198
	s_mul_i32 s14, s13, 0xc000
	v_add_u32_e32 v198, s14, v222
	ds_read_b128 v[216:219], v198 offset:1280
	ds_read_b32 v204, v199
	s_waitcnt lgkmcnt(0)
	v_fmac_f32_e32 v200, v212, v220
	v_fmac_f32_e32 v201, v213, v220
	v_fmac_f32_e32 v202, v214, v220
	v_fmac_f32_e32 v203, v215, v220
	v_fmac_f32_e32 v200, v216, v221
	v_fmac_f32_e32 v201, v217, v221
	v_fmac_f32_e32 v202, v218, v221
	v_fmac_f32_e32 v203, v219, v221
	v_cvt_pk_bf16_f32 v200, v200, v201
	v_cvt_pk_bf16_f32 v201, v202, v203
	global_store_dwordx2 v[190:191], v[200:201], off
	s_mov_b64 s[4:5], exec
	s_and_b64 exec, exec, s[40:41]
	s_cbranch_execz .Lh_nobeta_last
	global_store_dword v[192:193], v204, off

.LBB0_606:
	s_and_b64 vcc, exec, s[0:1]
	s_cbranch_vccz .LBB0_508
	s_waitcnt vmcnt(0)
	v_lshrrev_b32_e32 v90, 4, v241
	v_bfe_u32 v91, v241, 3, 1
	v_and_b32_e32 v86, 15, v241
	v_lshlrev_b32_e32 v90, 1, v90
	v_lshlrev_b32_e32 v86, 4, v86
	v_add_u32_e32 v92, v90, v91
	v_xor_b32_e32 v91, 1, v91
	v_add_u32_e32 v93, v90, v91
	s_lshl_b32 s0, s10, 5
	v_lshlrev_b32_e32 v89, 2, v92
	v_add_u32_e32 v92, s0, v92
	v_add_u32_e32 v93, s0, v93
	v_add_u32_e32 v89, 0x18000, v89
	v_lshlrev_b32_e32 v87, 2, v92
	v_lshlrev_b32_e32 v88, 2, v93
	v_mov_b32_e32 v0, 0
	v_mov_b32_e32 v1, 0
	v_mov_b32_e32 v2, 0
	v_mov_b32_e32 v3, 0
	v_mov_b32_e32 v4, 0
	v_mov_b32_e32 v5, 0
	v_mov_b32_e32 v6, 0
	v_mov_b32_e32 v7, 0
	s_waitcnt lgkmcnt(0)
	s_barrier
	s_mov_b32 s4, 0
	s_nop 0
	s_nop 0
	s_nop 0
	s_nop 0
	s_nop 0
.Lrec_chunk:
	s_and_b32 s0, s4, 1
	s_mul_i32 s1, s0, 0xc000
	s_lshl_b32 s5, s0, 8
	v_add_u32_e32 v80, s1, v86
	v_add_u32_e32 v81, s1, v87
	v_add_u32_e32 v82, s1, v88
	s_add_i32 s5, s5, 0x1a100
	s_lshl_b32 s0, s0, 12
	v_mov_b32_e32 v83, s5
	v_add_u32_e32 v84, s0, v89
	ds_read_b128 v[12:15], v80 offset:768
	ds_read_b128 v[16:19], v80 offset:0
	ds_read_b128 v[20:23], v80 offset:256
	ds_read_b128 v[24:27], v80 offset:512
	ds_read_b128 v[28:31], v80 offset:1024
	ds_read_b32 v32, v81 offset:1280
	ds_read_b32 v33, v82 offset:1280
	s_waitcnt lgkmcnt(5)
	v_pk_mul_f32 v[8:9], v[0:1], v[12:13] op_sel_hi:[1,0]
	v_pk_mul_f32 v[10:11], v[0:1], v[16:17] op_sel_hi:[1,0]
	ds_read_b128 v[40:43], v80 offset:2304
	v_pk_fma_f32 v[8:9], v[2:3], v[12:13], v[8:9] op_sel:[0,1,0]
	v_pk_fma_f32 v[10:11], v[2:3], v[16:17], v[10:11] op_sel:[0,1,0]
	ds_read_b128 v[44:47], v80 offset:1536
	v_pk_fma_f32 v[8:9], v[4:5], v[14:15], v[8:9] op_sel_hi:[1,0,1]
	v_pk_fma_f32 v[10:11], v[4:5], v[18:19], v[10:11] op_sel_hi:[1,0,1]
	ds_read_b128 v[48:51], v80 offset:1792
	v_pk_fma_f32 v[8:9], v[6:7], v[14:15], v[8:9] op_sel:[0,1,0]
	v_pk_fma_f32 v[10:11], v[6:7], v[18:19], v[10:11] op_sel:[0,1,0]
	ds_read_b128 v[52:55], v80 offset:2048
	v_add_f32_dpp v74, v9, v8 row_ror:8 row_mask:0xf bank_mask:0xf bound_ctrl:1
	v_add_f32_dpp v75, v11, v10 row_ror:8 row_mask:0xf bank_mask:0xf bound_ctrl:1
	ds_read_b128 v[56:59], v80 offset:2560
	v_add_f32_dpp v74, v74, v74 quad_perm:[1,0,3,2] row_mask:0xf bank_mask:0xf bound_ctrl:1
	v_add_f32_dpp v75, v75, v75 quad_perm:[1,0,3,2] row_mask:0xf bank_mask:0xf bound_ctrl:1
	ds_read_b32 v60, v81 offset:2816
	v_add_f32_dpp v74, v74, v74 quad_perm:[2,3,0,1] row_mask:0xf bank_mask:0xf bound_ctrl:1
	v_add_f32_dpp v75, v75, v75 quad_perm:[2,3,0,1] row_mask:0xf bank_mask:0xf bound_ctrl:1
	ds_read_b32 v61, v82 offset:2816
	v_add_f32_dpp v76, v74, v74 row_half_mirror row_mask:0xf bank_mask:0xf bound_ctrl:1
	v_add_f32_dpp v36, v75, v75 row_half_mirror row_mask:0xf bank_mask:0xf bound_ctrl:1
	s_nop 0
	v_mov_b32_dpp v77, v76 row_ror:8 row_mask:0xf bank_mask:0xf bound_ctrl:1
	s_waitcnt lgkmcnt(7)
	v_pk_mul_f32 v[66:67], v[76:77], v[28:29] op_sel_hi:[1,0]
	v_pk_mul_f32 v[68:69], v[76:77], v[28:29] op_sel:[0,1]
	v_pk_mul_f32 v[70:71], v[76:77], v[30:31] op_sel_hi:[1,0]
	v_pk_mul_f32 v[72:73], v[76:77], v[30:31] op_sel:[0,1]
	v_pk_fma_f32 v[66:67], v[32:33], v[24:25], v[66:67] op_sel_hi:[1,0,1]
	v_pk_fma_f32 v[68:69], v[32:33], v[24:25], v[68:69] op_sel:[0,1,0]
	v_pk_fma_f32 v[70:71], v[32:33], v[26:27], v[70:71] op_sel_hi:[1,0,1]
	v_pk_fma_f32 v[72:73], v[32:33], v[26:27], v[72:73] op_sel:[0,1,0]
	v_pk_fma_f32 v[0:1], v[0:1], v[20:21], v[66:67] op_sel_hi:[1,0,1]
	v_pk_fma_f32 v[2:3], v[2:3], v[20:21], v[68:69] op_sel:[0,1,0]
	v_pk_fma_f32 v[4:5], v[4:5], v[22:23], v[70:71] op_sel_hi:[1,0,1]
	v_pk_fma_f32 v[6:7], v[6:7], v[22:23], v[72:73] op_sel:[0,1,0]
	ds_write_b32 v84, v36 offset:0
	ds_write_b32 v84, v76 offset:12288
	s_waitcnt lgkmcnt(7)
	v_pk_mul_f32 v[8:9], v[0:1], v[40:41] op_sel_hi:[1,0]
	v_pk_mul_f32 v[10:11], v[0:1], v[44:45] op_sel_hi:[1,0]
	ds_read_b128 v[12:15], v80 offset:3840
	v_pk_fma_f32 v[8:9], v[2:3], v[40:41], v[8:9] op_sel:[0,1,0]
	v_pk_fma_f32 v[10:11], v[2:3], v[44:45], v[10:11] op_sel:[0,1,0]
	ds_read_b128 v[16:19], v80 offset:3072
	v_pk_fma_f32 v[8:9], v[4:5], v[42:43], v[8:9] op_sel_hi:[1,0,1]
	v_pk_fma_f32 v[10:11], v[4:5], v[46:47], v[10:11] op_sel_hi:[1,0,1]
	ds_read_b128 v[20:23], v80 offset:3328
	v_pk_fma_f32 v[8:9], v[6:7], v[42:43], v[8:9] op_sel:[0,1,0]
	v_pk_fma_f32 v[10:11], v[6:7], v[46:47], v[10:11] op_sel:[0,1,0]
	ds_read_b128 v[24:27], v80 offset:3584
	v_add_f32_dpp v74, v9, v8 row_ror:8 row_mask:0xf bank_mask:0xf bound_ctrl:1
	v_add_f32_dpp v75, v11, v10 row_ror:8 row_mask:0xf bank_mask:0xf bound_ctrl:1
	ds_read_b128 v[28:31], v80 offset:4096
	v_add_f32_dpp v74, v74, v74 quad_perm:[1,0,3,2] row_mask:0xf bank_mask:0xf bound_ctrl:1
	v_add_f32_dpp v75, v75, v75 quad_perm:[1,0,3,2] row_mask:0xf bank_mask:0xf bound_ctrl:1
	ds_read_b32 v32, v81 offset:4352
	v_add_f32_dpp v74, v74, v74 quad_perm:[2,3,0,1] row_mask:0xf bank_mask:0xf bound_ctrl:1
	v_add_f32_dpp v75, v75, v75 quad_perm:[2,3,0,1] row_mask:0xf bank_mask:0xf bound_ctrl:1
	ds_read_b32 v33, v82 offset:4352
	v_add_f32_dpp v76, v74, v74 row_half_mirror row_mask:0xf bank_mask:0xf bound_ctrl:1
	v_add_f32_dpp v64, v75, v75 row_half_mirror row_mask:0xf bank_mask:0xf bound_ctrl:1
	s_nop 0
	v_mov_b32_dpp v77, v76 row_ror:8 row_mask:0xf bank_mask:0xf bound_ctrl:1
	s_waitcnt lgkmcnt(9)
	v_pk_mul_f32 v[66:67], v[76:77], v[56:57] op_sel_hi:[1,0]
	v_pk_mul_f32 v[68:69], v[76:77], v[56:57] op_sel:[0,1]
	v_pk_mul_f32 v[70:71], v[76:77], v[58:59] op_sel_hi:[1,0]
	v_pk_mul_f32 v[72:73], v[76:77], v[58:59] op_sel:[0,1]
	v_pk_fma_f32 v[66:67], v[60:61], v[52:53], v[66:67] op_sel_hi:[1,0,1]
	v_pk_fma_f32 v[68:69], v[60:61], v[52:53], v[68:69] op_sel:[0,1,0]
	v_pk_fma_f32 v[70:71], v[60:61], v[54:55], v[70:71] op_sel_hi:[1,0,1]
	v_pk_fma_f32 v[72:73], v[60:61], v[54:55], v[72:73] op_sel:[0,1,0]
	v_pk_fma_f32 v[0:1], v[0:1], v[48:49], v[66:67] op_sel_hi:[1,0,1]
	v_pk_fma_f32 v[2:3], v[2:3], v[48:49], v[68:69] op_sel:[0,1,0]
	v_pk_fma_f32 v[4:5], v[4:5], v[50:51], v[70:71] op_sel_hi:[1,0,1]
	v_pk_fma_f32 v[6:7], v[6:7], v[50:51], v[72:73] op_sel:[0,1,0]
	ds_write_b32 v84, v64 offset:128
	ds_write_b32 v84, v76 offset:12416
	s_waitcnt lgkmcnt(7)
	v_pk_mul_f32 v[8:9], v[0:1], v[12:13] op_sel_hi:[1,0]
	v_pk_mul_f32 v[10:11], v[0:1], v[16:17] op_sel_hi:[1,0]
	ds_read_b128 v[40:43], v80 offset:5376
	v_pk_fma_f32 v[8:9], v[2:3], v[12:13], v[8:9] op_sel:[0,1,0]
	v_pk_fma_f32 v[10:11], v[2:3], v[16:17], v[10:11] op_sel:[0,1,0]
	ds_read_b128 v[44:47], v80 offset:4608
	v_pk_fma_f32 v[8:9], v[4:5], v[14:15], v[8:9] op_sel_hi:[1,0,1]
	v_pk_fma_f32 v[10:11], v[4:5], v[18:19], v[10:11] op_sel_hi:[1,0,1]
	ds_read_b128 v[48:51], v80 offset:4864
	v_pk_fma_f32 v[8:9], v[6:7], v[14:15], v[8:9] op_sel:[0,1,0]
	v_pk_fma_f32 v[10:11], v[6:7], v[18:19], v[10:11] op_sel:[0,1,0]
	ds_read_b128 v[52:55], v80 offset:5120
	v_add_f32_dpp v74, v9, v8 row_ror:8 row_mask:0xf bank_mask:0xf bound_ctrl:1
	v_add_f32_dpp v75, v11, v10 row_ror:8 row_mask:0xf bank_mask:0xf bound_ctrl:1
	ds_read_b128 v[56:59], v80 offset:5632
	v_add_f32_dpp v74, v74, v74 quad_perm:[1,0,3,2] row_mask:0xf bank_mask:0xf bound_ctrl:1
	v_add_f32_dpp v75, v75, v75 quad_perm:[1,0,3,2] row_mask:0xf bank_mask:0xf bound_ctrl:1
	ds_read_b32 v60, v81 offset:5888
	v_add_f32_dpp v74, v74, v74 quad_perm:[2,3,0,1] row_mask:0xf bank_mask:0xf bound_ctrl:1
	v_add_f32_dpp v75, v75, v75 quad_perm:[2,3,0,1] row_mask:0xf bank_mask:0xf bound_ctrl:1
	ds_read_b32 v61, v82 offset:5888
	v_add_f32_dpp v76, v74, v74 row_half_mirror row_mask:0xf bank_mask:0xf bound_ctrl:1
	v_add_f32_dpp v36, v75, v75 row_half_mirror row_mask:0xf bank_mask:0xf bound_ctrl:1
	s_nop 0
	v_mov_b32_dpp v77, v76 row_ror:8 row_mask:0xf bank_mask:0xf bound_ctrl:1
	s_waitcnt lgkmcnt(9)
	v_pk_mul_f32 v[66:67], v[76:77], v[28:29] op_sel_hi:[1,0]
	v_pk_mul_f32 v[68:69], v[76:77], v[28:29] op_sel:[0,1]
	v_pk_mul_f32 v[70:71], v[76:77], v[30:31] op_sel_hi:[1,0]
	v_pk_mul_f32 v[72:73], v[76:77], v[30:31] op_sel:[0,1]
	v_pk_fma_f32 v[66:67], v[32:33], v[24:25], v[66:67] op_sel_hi:[1,0,1]
	v_pk_fma_f32 v[68:69], v[32:33], v[24:25], v[68:69] op_sel:[0,1,0]
	v_pk_fma_f32 v[70:71], v[32:33], v[26:27], v[70:71] op_sel_hi:[1,0,1]
	v_pk_fma_f32 v[72:73], v[32:33], v[26:27], v[72:73] op_sel:[0,1,0]
	v_pk_fma_f32 v[0:1], v[0:1], v[20:21], v[66:67] op_sel_hi:[1,0,1]
	v_pk_fma_f32 v[2:3], v[2:3], v[20:21], v[68:69] op_sel:[0,1,0]
	v_pk_fma_f32 v[4:5], v[4:5], v[22:23], v[70:71] op_sel_hi:[1,0,1]
	v_pk_fma_f32 v[6:7], v[6:7], v[22:23], v[72:73] op_sel:[0,1,0]
	ds_write_b32 v84, v36 offset:256
	ds_write_b32 v84, v76 offset:12544
	s_waitcnt lgkmcnt(7)
	v_pk_mul_f32 v[8:9], v[0:1], v[40:41] op_sel_hi:[1,0]
	v_pk_mul_f32 v[10:11], v[0:1], v[44:45] op_sel_hi:[1,0]
	ds_read_b128 v[12:15], v80 offset:6912
	v_pk_fma_f32 v[8:9], v[2:3], v[40:41], v[8:9] op_sel:[0,1,0]
	v_pk_fma_f32 v[10:11], v[2:3], v[44:45], v[10:11] op_sel:[0,1,0]
	ds_read_b128 v[16:19], v80 offset:6144
	v_pk_fma_f32 v[8:9], v[4:5], v[42:43], v[8:9] op_sel_hi:[1,0,1]
	v_pk_fma_f32 v[10:11], v[4:5], v[46:47], v[10:11] op_sel_hi:[1,0,1]
	ds_read_b128 v[20:23], v80 offset:6400
	v_pk_fma_f32 v[8:9], v[6:7], v[42:43], v[8:9] op_sel:[0,1,0]
	v_pk_fma_f32 v[10:11], v[6:7], v[46:47], v[10:11] op_sel:[0,1,0]
	ds_read_b128 v[24:27], v80 offset:6656
	v_add_f32_dpp v74, v9, v8 row_ror:8 row_mask:0xf bank_mask:0xf bound_ctrl:1
	v_add_f32_dpp v75, v11, v10 row_ror:8 row_mask:0xf bank_mask:0xf bound_ctrl:1
	ds_read_b128 v[28:31], v80 offset:7168
	v_add_f32_dpp v74, v74, v74 quad_perm:[1,0,3,2] row_mask:0xf bank_mask:0xf bound_ctrl:1
	v_add_f32_dpp v75, v75, v75 quad_perm:[1,0,3,2] row_mask:0xf bank_mask:0xf bound_ctrl:1
	ds_read_b32 v32, v81 offset:7424
	v_add_f32_dpp v74, v74, v74 quad_perm:[2,3,0,1] row_mask:0xf bank_mask:0xf bound_ctrl:1
	v_add_f32_dpp v75, v75, v75 quad_perm:[2,3,0,1] row_mask:0xf bank_mask:0xf bound_ctrl:1
	ds_read_b32 v33, v82 offset:7424
	v_add_f32_dpp v76, v74, v74 row_half_mirror row_mask:0xf bank_mask:0xf bound_ctrl:1
	v_add_f32_dpp v64, v75, v75 row_half_mirror row_mask:0xf bank_mask:0xf bound_ctrl:1
	s_nop 0
	v_mov_b32_dpp v77, v76 row_ror:8 row_mask:0xf bank_mask:0xf bound_ctrl:1
	s_waitcnt lgkmcnt(9)
	v_pk_mul_f32 v[66:67], v[76:77], v[56:57] op_sel_hi:[1,0]
	v_pk_mul_f32 v[68:69], v[76:77], v[56:57] op_sel:[0,1]
	v_pk_mul_f32 v[70:71], v[76:77], v[58:59] op_sel_hi:[1,0]
	v_pk_mul_f32 v[72:73], v[76:77], v[58:59] op_sel:[0,1]
	v_pk_fma_f32 v[66:67], v[60:61], v[52:53], v[66:67] op_sel_hi:[1,0,1]
	v_pk_fma_f32 v[68:69], v[60:61], v[52:53], v[68:69] op_sel:[0,1,0]
	v_pk_fma_f32 v[70:71], v[60:61], v[54:55], v[70:71] op_sel_hi:[1,0,1]
	v_pk_fma_f32 v[72:73], v[60:61], v[54:55], v[72:73] op_sel:[0,1,0]
	v_pk_fma_f32 v[0:1], v[0:1], v[48:49], v[66:67] op_sel_hi:[1,0,1]
	v_pk_fma_f32 v[2:3], v[2:3], v[48:49], v[68:69] op_sel:[0,1,0]
	v_pk_fma_f32 v[4:5], v[4:5], v[50:51], v[70:71] op_sel_hi:[1,0,1]
	v_pk_fma_f32 v[6:7], v[6:7], v[50:51], v[72:73] op_sel:[0,1,0]
	ds_write_b32 v84, v64 offset:384
	ds_write_b32 v84, v76 offset:12672
	s_waitcnt lgkmcnt(7)
	v_pk_mul_f32 v[8:9], v[0:1], v[12:13] op_sel_hi:[1,0]
	v_pk_mul_f32 v[10:11], v[0:1], v[16:17] op_sel_hi:[1,0]
	ds_read_b128 v[40:43], v80 offset:8448
	v_pk_fma_f32 v[8:9], v[2:3], v[12:13], v[8:9] op_sel:[0,1,0]
	v_pk_fma_f32 v[10:11], v[2:3], v[16:17], v[10:11] op_sel:[0,1,0]
	ds_read_b128 v[44:47], v80 offset:7680
	v_pk_fma_f32 v[8:9], v[4:5], v[14:15], v[8:9] op_sel_hi:[1,0,1]
	v_pk_fma_f32 v[10:11], v[4:5], v[18:19], v[10:11] op_sel_hi:[1,0,1]
	ds_read_b128 v[48:51], v80 offset:7936
	v_pk_fma_f32 v[8:9], v[6:7], v[14:15], v[8:9] op_sel:[0,1,0]
	v_pk_fma_f32 v[10:11], v[6:7], v[18:19], v[10:11] op_sel:[0,1,0]
	ds_read_b128 v[52:55], v80 offset:8192
	v_add_f32_dpp v74, v9, v8 row_ror:8 row_mask:0xf bank_mask:0xf bound_ctrl:1
	v_add_f32_dpp v75, v11, v10 row_ror:8 row_mask:0xf bank_mask:0xf bound_ctrl:1
	ds_read_b128 v[56:59], v80 offset:8704
	v_add_f32_dpp v74, v74, v74 quad_perm:[1,0,3,2] row_mask:0xf bank_mask:0xf bound_ctrl:1
	v_add_f32_dpp v75, v75, v75 quad_perm:[1,0,3,2] row_mask:0xf bank_mask:0xf bound_ctrl:1
	ds_read_b32 v60, v81 offset:8960
	v_add_f32_dpp v74, v74, v74 quad_perm:[2,3,0,1] row_mask:0xf bank_mask:0xf bound_ctrl:1
	v_add_f32_dpp v75, v75, v75 quad_perm:[2,3,0,1] row_mask:0xf bank_mask:0xf bound_ctrl:1
	ds_read_b32 v61, v82 offset:8960
	v_add_f32_dpp v76, v74, v74 row_half_mirror row_mask:0xf bank_mask:0xf bound_ctrl:1
	v_add_f32_dpp v36, v75, v75 row_half_mirror row_mask:0xf bank_mask:0xf bound_ctrl:1
	s_nop 0
	v_mov_b32_dpp v77, v76 row_ror:8 row_mask:0xf bank_mask:0xf bound_ctrl:1
	s_waitcnt lgkmcnt(9)
	v_pk_mul_f32 v[66:67], v[76:77], v[28:29] op_sel_hi:[1,0]
	v_pk_mul_f32 v[68:69], v[76:77], v[28:29] op_sel:[0,1]
	v_pk_mul_f32 v[70:71], v[76:77], v[30:31] op_sel_hi:[1,0]
	v_pk_mul_f32 v[72:73], v[76:77], v[30:31] op_sel:[0,1]
	v_pk_fma_f32 v[66:67], v[32:33], v[24:25], v[66:67] op_sel_hi:[1,0,1]
	v_pk_fma_f32 v[68:69], v[32:33], v[24:25], v[68:69] op_sel:[0,1,0]
	v_pk_fma_f32 v[70:71], v[32:33], v[26:27], v[70:71] op_sel_hi:[1,0,1]
	v_pk_fma_f32 v[72:73], v[32:33], v[26:27], v[72:73] op_sel:[0,1,0]
	v_pk_fma_f32 v[0:1], v[0:1], v[20:21], v[66:67] op_sel_hi:[1,0,1]
	v_pk_fma_f32 v[2:3], v[2:3], v[20:21], v[68:69] op_sel:[0,1,0]
	v_pk_fma_f32 v[4:5], v[4:5], v[22:23], v[70:71] op_sel_hi:[1,0,1]
	v_pk_fma_f32 v[6:7], v[6:7], v[22:23], v[72:73] op_sel:[0,1,0]
	ds_write_b32 v84, v36 offset:512
	ds_write_b32 v84, v76 offset:12800
	s_waitcnt lgkmcnt(7)
	v_pk_mul_f32 v[8:9], v[0:1], v[40:41] op_sel_hi:[1,0]
	v_pk_mul_f32 v[10:11], v[0:1], v[44:45] op_sel_hi:[1,0]
	ds_read_b128 v[12:15], v80 offset:9984
	v_pk_fma_f32 v[8:9], v[2:3], v[40:41], v[8:9] op_sel:[0,1,0]
	v_pk_fma_f32 v[10:11], v[2:3], v[44:45], v[10:11] op_sel:[0,1,0]
	ds_read_b128 v[16:19], v80 offset:9216
	v_pk_fma_f32 v[8:9], v[4:5], v[42:43], v[8:9] op_sel_hi:[1,0,1]
	v_pk_fma_f32 v[10:11], v[4:5], v[46:47], v[10:11] op_sel_hi:[1,0,1]
	ds_read_b128 v[20:23], v80 offset:9472
	v_pk_fma_f32 v[8:9], v[6:7], v[42:43], v[8:9] op_sel:[0,1,0]
	v_pk_fma_f32 v[10:11], v[6:7], v[46:47], v[10:11] op_sel:[0,1,0]
	ds_read_b128 v[24:27], v80 offset:9728
	v_add_f32_dpp v74, v9, v8 row_ror:8 row_mask:0xf bank_mask:0xf bound_ctrl:1
	v_add_f32_dpp v75, v11, v10 row_ror:8 row_mask:0xf bank_mask:0xf bound_ctrl:1
	ds_read_b128 v[28:31], v80 offset:10240
	v_add_f32_dpp v74, v74, v74 quad_perm:[1,0,3,2] row_mask:0xf bank_mask:0xf bound_ctrl:1
	v_add_f32_dpp v75, v75, v75 quad_perm:[1,0,3,2] row_mask:0xf bank_mask:0xf bound_ctrl:1
	ds_read_b32 v32, v81 offset:10496
	v_add_f32_dpp v74, v74, v74 quad_perm:[2,3,0,1] row_mask:0xf bank_mask:0xf bound_ctrl:1
	v_add_f32_dpp v75, v75, v75 quad_perm:[2,3,0,1] row_mask:0xf bank_mask:0xf bound_ctrl:1
	ds_read_b32 v33, v82 offset:10496
	v_add_f32_dpp v76, v74, v74 row_half_mirror row_mask:0xf bank_mask:0xf bound_ctrl:1
	v_add_f32_dpp v64, v75, v75 row_half_mirror row_mask:0xf bank_mask:0xf bound_ctrl:1
	s_nop 0
	v_mov_b32_dpp v77, v76 row_ror:8 row_mask:0xf bank_mask:0xf bound_ctrl:1
	s_waitcnt lgkmcnt(9)
	v_pk_mul_f32 v[66:67], v[76:77], v[56:57] op_sel_hi:[1,0]
	v_pk_mul_f32 v[68:69], v[76:77], v[56:57] op_sel:[0,1]
	v_pk_mul_f32 v[70:71], v[76:77], v[58:59] op_sel_hi:[1,0]
	v_pk_mul_f32 v[72:73], v[76:77], v[58:59] op_sel:[0,1]
	v_pk_fma_f32 v[66:67], v[60:61], v[52:53], v[66:67] op_sel_hi:[1,0,1]
	v_pk_fma_f32 v[68:69], v[60:61], v[52:53], v[68:69] op_sel:[0,1,0]
	v_pk_fma_f32 v[70:71], v[60:61], v[54:55], v[70:71] op_sel_hi:[1,0,1]
	v_pk_fma_f32 v[72:73], v[60:61], v[54:55], v[72:73] op_sel:[0,1,0]
	v_pk_fma_f32 v[0:1], v[0:1], v[48:49], v[66:67] op_sel_hi:[1,0,1]
	v_pk_fma_f32 v[2:3], v[2:3], v[48:49], v[68:69] op_sel:[0,1,0]
	v_pk_fma_f32 v[4:5], v[4:5], v[50:51], v[70:71] op_sel_hi:[1,0,1]
	v_pk_fma_f32 v[6:7], v[6:7], v[50:51], v[72:73] op_sel:[0,1,0]
	ds_write_b32 v84, v64 offset:640
	ds_write_b32 v84, v76 offset:12928
	s_waitcnt lgkmcnt(7)
	v_pk_mul_f32 v[8:9], v[0:1], v[12:13] op_sel_hi:[1,0]
	v_pk_mul_f32 v[10:11], v[0:1], v[16:17] op_sel_hi:[1,0]
	ds_read_b128 v[40:43], v80 offset:11520
	v_pk_fma_f32 v[8:9], v[2:3], v[12:13], v[8:9] op_sel:[0,1,0]
	v_pk_fma_f32 v[10:11], v[2:3], v[16:17], v[10:11] op_sel:[0,1,0]
	ds_read_b128 v[44:47], v80 offset:10752
	v_pk_fma_f32 v[8:9], v[4:5], v[14:15], v[8:9] op_sel_hi:[1,0,1]
	v_pk_fma_f32 v[10:11], v[4:5], v[18:19], v[10:11] op_sel_hi:[1,0,1]
	ds_read_b128 v[48:51], v80 offset:11008
	v_pk_fma_f32 v[8:9], v[6:7], v[14:15], v[8:9] op_sel:[0,1,0]
	v_pk_fma_f32 v[10:11], v[6:7], v[18:19], v[10:11] op_sel:[0,1,0]
	ds_read_b128 v[52:55], v80 offset:11264
	v_add_f32_dpp v74, v9, v8 row_ror:8 row_mask:0xf bank_mask:0xf bound_ctrl:1
	v_add_f32_dpp v75, v11, v10 row_ror:8 row_mask:0xf bank_mask:0xf bound_ctrl:1
	ds_read_b128 v[56:59], v80 offset:11776
	v_add_f32_dpp v74, v74, v74 quad_perm:[1,0,3,2] row_mask:0xf bank_mask:0xf bound_ctrl:1
	v_add_f32_dpp v75, v75, v75 quad_perm:[1,0,3,2] row_mask:0xf bank_mask:0xf bound_ctrl:1
	ds_read_b32 v60, v81 offset:12032
	v_add_f32_dpp v74, v74, v74 quad_perm:[2,3,0,1] row_mask:0xf bank_mask:0xf bound_ctrl:1
	v_add_f32_dpp v75, v75, v75 quad_perm:[2,3,0,1] row_mask:0xf bank_mask:0xf bound_ctrl:1
	ds_read_b32 v61, v82 offset:12032
	v_add_f32_dpp v76, v74, v74 row_half_mirror row_mask:0xf bank_mask:0xf bound_ctrl:1
	v_add_f32_dpp v36, v75, v75 row_half_mirror row_mask:0xf bank_mask:0xf bound_ctrl:1
	s_nop 0
	v_mov_b32_dpp v77, v76 row_ror:8 row_mask:0xf bank_mask:0xf bound_ctrl:1
	s_waitcnt lgkmcnt(9)
	v_pk_mul_f32 v[66:67], v[76:77], v[28:29] op_sel_hi:[1,0]
	v_pk_mul_f32 v[68:69], v[76:77], v[28:29] op_sel:[0,1]
	v_pk_mul_f32 v[70:71], v[76:77], v[30:31] op_sel_hi:[1,0]
	v_pk_mul_f32 v[72:73], v[76:77], v[30:31] op_sel:[0,1]
	v_pk_fma_f32 v[66:67], v[32:33], v[24:25], v[66:67] op_sel_hi:[1,0,1]
	v_pk_fma_f32 v[68:69], v[32:33], v[24:25], v[68:69] op_sel:[0,1,0]
	v_pk_fma_f32 v[70:71], v[32:33], v[26:27], v[70:71] op_sel_hi:[1,0,1]
	v_pk_fma_f32 v[72:73], v[32:33], v[26:27], v[72:73] op_sel:[0,1,0]
	v_pk_fma_f32 v[0:1], v[0:1], v[20:21], v[66:67] op_sel_hi:[1,0,1]
	v_pk_fma_f32 v[2:3], v[2:3], v[20:21], v[68:69] op_sel:[0,1,0]
	v_pk_fma_f32 v[4:5], v[4:5], v[22:23], v[70:71] op_sel_hi:[1,0,1]
	v_pk_fma_f32 v[6:7], v[6:7], v[22:23], v[72:73] op_sel:[0,1,0]
	ds_write_b32 v84, v36 offset:768
	ds_write_b32 v84, v76 offset:13056
	s_waitcnt lgkmcnt(7)
	v_pk_mul_f32 v[8:9], v[0:1], v[40:41] op_sel_hi:[1,0]
	v_pk_mul_f32 v[10:11], v[0:1], v[44:45] op_sel_hi:[1,0]
	ds_read_b128 v[12:15], v80 offset:13056
	v_pk_fma_f32 v[8:9], v[2:3], v[40:41], v[8:9] op_sel:[0,1,0]
	v_pk_fma_f32 v[10:11], v[2:3], v[44:45], v[10:11] op_sel:[0,1,0]
	ds_read_b128 v[16:19], v80 offset:12288
	v_pk_fma_f32 v[8:9], v[4:5], v[42:43], v[8:9] op_sel_hi:[1,0,1]
	v_pk_fma_f32 v[10:11], v[4:5], v[46:47], v[10:11] op_sel_hi:[1,0,1]
	ds_read_b128 v[20:23], v80 offset:12544
	v_pk_fma_f32 v[8:9], v[6:7], v[42:43], v[8:9] op_sel:[0,1,0]
	v_pk_fma_f32 v[10:11], v[6:7], v[46:47], v[10:11] op_sel:[0,1,0]
	ds_read_b128 v[24:27], v80 offset:12800
	v_add_f32_dpp v74, v9, v8 row_ror:8 row_mask:0xf bank_mask:0xf bound_ctrl:1
	v_add_f32_dpp v75, v11, v10 row_ror:8 row_mask:0xf bank_mask:0xf bound_ctrl:1
	ds_read_b128 v[28:31], v80 offset:13312
	v_add_f32_dpp v74, v74, v74 quad_perm:[1,0,3,2] row_mask:0xf bank_mask:0xf bound_ctrl:1
	v_add_f32_dpp v75, v75, v75 quad_perm:[1,0,3,2] row_mask:0xf bank_mask:0xf bound_ctrl:1
	ds_read_b32 v32, v81 offset:13568
	v_add_f32_dpp v74, v74, v74 quad_perm:[2,3,0,1] row_mask:0xf bank_mask:0xf bound_ctrl:1
	v_add_f32_dpp v75, v75, v75 quad_perm:[2,3,0,1] row_mask:0xf bank_mask:0xf bound_ctrl:1
	ds_read_b32 v33, v82 offset:13568
	v_add_f32_dpp v76, v74, v74 row_half_mirror row_mask:0xf bank_mask:0xf bound_ctrl:1
	v_add_f32_dpp v64, v75, v75 row_half_mirror row_mask:0xf bank_mask:0xf bound_ctrl:1
	s_nop 0
	v_mov_b32_dpp v77, v76 row_ror:8 row_mask:0xf bank_mask:0xf bound_ctrl:1
	s_waitcnt lgkmcnt(9)
	v_pk_mul_f32 v[66:67], v[76:77], v[56:57] op_sel_hi:[1,0]
	v_pk_mul_f32 v[68:69], v[76:77], v[56:57] op_sel:[0,1]
	v_pk_mul_f32 v[70:71], v[76:77], v[58:59] op_sel_hi:[1,0]
	v_pk_mul_f32 v[72:73], v[76:77], v[58:59] op_sel:[0,1]
	v_pk_fma_f32 v[66:67], v[60:61], v[52:53], v[66:67] op_sel_hi:[1,0,1]
	v_pk_fma_f32 v[68:69], v[60:61], v[52:53], v[68:69] op_sel:[0,1,0]
	v_pk_fma_f32 v[70:71], v[60:61], v[54:55], v[70:71] op_sel_hi:[1,0,1]
	v_pk_fma_f32 v[72:73], v[60:61], v[54:55], v[72:73] op_sel:[0,1,0]
	v_pk_fma_f32 v[0:1], v[0:1], v[48:49], v[66:67] op_sel_hi:[1,0,1]
	v_pk_fma_f32 v[2:3], v[2:3], v[48:49], v[68:69] op_sel:[0,1,0]
	v_pk_fma_f32 v[4:5], v[4:5], v[50:51], v[70:71] op_sel_hi:[1,0,1]
	v_pk_fma_f32 v[6:7], v[6:7], v[50:51], v[72:73] op_sel:[0,1,0]
	ds_write_b32 v84, v64 offset:896
	ds_write_b32 v84, v76 offset:13184
	s_waitcnt lgkmcnt(7)
	v_pk_mul_f32 v[8:9], v[0:1], v[12:13] op_sel_hi:[1,0]
	v_pk_mul_f32 v[10:11], v[0:1], v[16:17] op_sel_hi:[1,0]
	ds_read_b128 v[40:43], v80 offset:14592
	v_pk_fma_f32 v[8:9], v[2:3], v[12:13], v[8:9] op_sel:[0,1,0]
	v_pk_fma_f32 v[10:11], v[2:3], v[16:17], v[10:11] op_sel:[0,1,0]
	ds_read_b128 v[44:47], v80 offset:13824
	v_pk_fma_f32 v[8:9], v[4:5], v[14:15], v[8:9] op_sel_hi:[1,0,1]
	v_pk_fma_f32 v[10:11], v[4:5], v[18:19], v[10:11] op_sel_hi:[1,0,1]
	ds_read_b128 v[48:51], v80 offset:14080
	v_pk_fma_f32 v[8:9], v[6:7], v[14:15], v[8:9] op_sel:[0,1,0]
	v_pk_fma_f32 v[10:11], v[6:7], v[18:19], v[10:11] op_sel:[0,1,0]
	ds_read_b128 v[52:55], v80 offset:14336
	v_add_f32_dpp v74, v9, v8 row_ror:8 row_mask:0xf bank_mask:0xf bound_ctrl:1
	v_add_f32_dpp v75, v11, v10 row_ror:8 row_mask:0xf bank_mask:0xf bound_ctrl:1
	ds_read_b128 v[56:59], v80 offset:14848
	v_add_f32_dpp v74, v74, v74 quad_perm:[1,0,3,2] row_mask:0xf bank_mask:0xf bound_ctrl:1
	v_add_f32_dpp v75, v75, v75 quad_perm:[1,0,3,2] row_mask:0xf bank_mask:0xf bound_ctrl:1
	ds_read_b32 v60, v81 offset:15104
	v_add_f32_dpp v74, v74, v74 quad_perm:[2,3,0,1] row_mask:0xf bank_mask:0xf bound_ctrl:1
	v_add_f32_dpp v75, v75, v75 quad_perm:[2,3,0,1] row_mask:0xf bank_mask:0xf bound_ctrl:1
	ds_read_b32 v61, v82 offset:15104
	v_add_f32_dpp v76, v74, v74 row_half_mirror row_mask:0xf bank_mask:0xf bound_ctrl:1
	v_add_f32_dpp v36, v75, v75 row_half_mirror row_mask:0xf bank_mask:0xf bound_ctrl:1
	s_nop 0
	v_mov_b32_dpp v77, v76 row_ror:8 row_mask:0xf bank_mask:0xf bound_ctrl:1
	s_waitcnt lgkmcnt(9)
	v_pk_mul_f32 v[66:67], v[76:77], v[28:29] op_sel_hi:[1,0]
	v_pk_mul_f32 v[68:69], v[76:77], v[28:29] op_sel:[0,1]
	v_pk_mul_f32 v[70:71], v[76:77], v[30:31] op_sel_hi:[1,0]
	v_pk_mul_f32 v[72:73], v[76:77], v[30:31] op_sel:[0,1]
	v_pk_fma_f32 v[66:67], v[32:33], v[24:25], v[66:67] op_sel_hi:[1,0,1]
	v_pk_fma_f32 v[68:69], v[32:33], v[24:25], v[68:69] op_sel:[0,1,0]
	v_pk_fma_f32 v[70:71], v[32:33], v[26:27], v[70:71] op_sel_hi:[1,0,1]
	v_pk_fma_f32 v[72:73], v[32:33], v[26:27], v[72:73] op_sel:[0,1,0]
	v_pk_fma_f32 v[0:1], v[0:1], v[20:21], v[66:67] op_sel_hi:[1,0,1]
	v_pk_fma_f32 v[2:3], v[2:3], v[20:21], v[68:69] op_sel:[0,1,0]
	v_pk_fma_f32 v[4:5], v[4:5], v[22:23], v[70:71] op_sel_hi:[1,0,1]
	v_pk_fma_f32 v[6:7], v[6:7], v[22:23], v[72:73] op_sel:[0,1,0]
	ds_write_b32 v84, v36 offset:1024
	ds_write_b32 v84, v76 offset:13312
	s_waitcnt lgkmcnt(7)
	v_pk_mul_f32 v[8:9], v[0:1], v[40:41] op_sel_hi:[1,0]
	v_pk_mul_f32 v[10:11], v[0:1], v[44:45] op_sel_hi:[1,0]
	ds_read_b128 v[12:15], v80 offset:16128
	v_pk_fma_f32 v[8:9], v[2:3], v[40:41], v[8:9] op_sel:[0,1,0]
	v_pk_fma_f32 v[10:11], v[2:3], v[44:45], v[10:11] op_sel:[0,1,0]
	ds_read_b128 v[16:19], v80 offset:15360
	v_pk_fma_f32 v[8:9], v[4:5], v[42:43], v[8:9] op_sel_hi:[1,0,1]
	v_pk_fma_f32 v[10:11], v[4:5], v[46:47], v[10:11] op_sel_hi:[1,0,1]
	ds_read_b128 v[20:23], v80 offset:15616
	v_pk_fma_f32 v[8:9], v[6:7], v[42:43], v[8:9] op_sel:[0,1,0]
	v_pk_fma_f32 v[10:11], v[6:7], v[46:47], v[10:11] op_sel:[0,1,0]
	ds_read_b128 v[24:27], v80 offset:15872
	v_add_f32_dpp v74, v9, v8 row_ror:8 row_mask:0xf bank_mask:0xf bound_ctrl:1
	v_add_f32_dpp v75, v11, v10 row_ror:8 row_mask:0xf bank_mask:0xf bound_ctrl:1
	ds_read_b128 v[28:31], v80 offset:16384
	v_add_f32_dpp v74, v74, v74 quad_perm:[1,0,3,2] row_mask:0xf bank_mask:0xf bound_ctrl:1
	v_add_f32_dpp v75, v75, v75 quad_perm:[1,0,3,2] row_mask:0xf bank_mask:0xf bound_ctrl:1
	ds_read_b32 v32, v81 offset:16640
	v_add_f32_dpp v74, v74, v74 quad_perm:[2,3,0,1] row_mask:0xf bank_mask:0xf bound_ctrl:1
	v_add_f32_dpp v75, v75, v75 quad_perm:[2,3,0,1] row_mask:0xf bank_mask:0xf bound_ctrl:1
	ds_read_b32 v33, v82 offset:16640
	v_add_f32_dpp v76, v74, v74 row_half_mirror row_mask:0xf bank_mask:0xf bound_ctrl:1
	v_add_f32_dpp v64, v75, v75 row_half_mirror row_mask:0xf bank_mask:0xf bound_ctrl:1
	s_nop 0
	v_mov_b32_dpp v77, v76 row_ror:8 row_mask:0xf bank_mask:0xf bound_ctrl:1
	s_waitcnt lgkmcnt(9)
	v_pk_mul_f32 v[66:67], v[76:77], v[56:57] op_sel_hi:[1,0]
	v_pk_mul_f32 v[68:69], v[76:77], v[56:57] op_sel:[0,1]
	v_pk_mul_f32 v[70:71], v[76:77], v[58:59] op_sel_hi:[1,0]
	v_pk_mul_f32 v[72:73], v[76:77], v[58:59] op_sel:[0,1]
	v_pk_fma_f32 v[66:67], v[60:61], v[52:53], v[66:67] op_sel_hi:[1,0,1]
	v_pk_fma_f32 v[68:69], v[60:61], v[52:53], v[68:69] op_sel:[0,1,0]
	v_pk_fma_f32 v[70:71], v[60:61], v[54:55], v[70:71] op_sel_hi:[1,0,1]
	v_pk_fma_f32 v[72:73], v[60:61], v[54:55], v[72:73] op_sel:[0,1,0]
	v_pk_fma_f32 v[0:1], v[0:1], v[48:49], v[66:67] op_sel_hi:[1,0,1]
	v_pk_fma_f32 v[2:3], v[2:3], v[48:49], v[68:69] op_sel:[0,1,0]
	v_pk_fma_f32 v[4:5], v[4:5], v[50:51], v[70:71] op_sel_hi:[1,0,1]
	v_pk_fma_f32 v[6:7], v[6:7], v[50:51], v[72:73] op_sel:[0,1,0]
	ds_write_b32 v84, v64 offset:1152
	ds_write_b32 v84, v76 offset:13440
	s_waitcnt lgkmcnt(7)
	v_pk_mul_f32 v[8:9], v[0:1], v[12:13] op_sel_hi:[1,0]
	v_pk_mul_f32 v[10:11], v[0:1], v[16:17] op_sel_hi:[1,0]
	ds_read_b128 v[40:43], v80 offset:17664
	v_pk_fma_f32 v[8:9], v[2:3], v[12:13], v[8:9] op_sel:[0,1,0]
	v_pk_fma_f32 v[10:11], v[2:3], v[16:17], v[10:11] op_sel:[0,1,0]
	ds_read_b128 v[44:47], v80 offset:16896
	v_pk_fma_f32 v[8:9], v[4:5], v[14:15], v[8:9] op_sel_hi:[1,0,1]
	v_pk_fma_f32 v[10:11], v[4:5], v[18:19], v[10:11] op_sel_hi:[1,0,1]
	ds_read_b128 v[48:51], v80 offset:17152
	v_pk_fma_f32 v[8:9], v[6:7], v[14:15], v[8:9] op_sel:[0,1,0]
	v_pk_fma_f32 v[10:11], v[6:7], v[18:19], v[10:11] op_sel:[0,1,0]
	ds_read_b128 v[52:55], v80 offset:17408
	v_add_f32_dpp v74, v9, v8 row_ror:8 row_mask:0xf bank_mask:0xf bound_ctrl:1
	v_add_f32_dpp v75, v11, v10 row_ror:8 row_mask:0xf bank_mask:0xf bound_ctrl:1
	ds_read_b128 v[56:59], v80 offset:17920
	v_add_f32_dpp v74, v74, v74 quad_perm:[1,0,3,2] row_mask:0xf bank_mask:0xf bound_ctrl:1
	v_add_f32_dpp v75, v75, v75 quad_perm:[1,0,3,2] row_mask:0xf bank_mask:0xf bound_ctrl:1
	ds_read_b32 v60, v81 offset:18176
	v_add_f32_dpp v74, v74, v74 quad_perm:[2,3,0,1] row_mask:0xf bank_mask:0xf bound_ctrl:1
	v_add_f32_dpp v75, v75, v75 quad_perm:[2,3,0,1] row_mask:0xf bank_mask:0xf bound_ctrl:1
	ds_read_b32 v61, v82 offset:18176
	v_add_f32_dpp v76, v74, v74 row_half_mirror row_mask:0xf bank_mask:0xf bound_ctrl:1
	v_add_f32_dpp v36, v75, v75 row_half_mirror row_mask:0xf bank_mask:0xf bound_ctrl:1
	s_nop 0
	v_mov_b32_dpp v77, v76 row_ror:8 row_mask:0xf bank_mask:0xf bound_ctrl:1
	s_waitcnt lgkmcnt(9)
	v_pk_mul_f32 v[66:67], v[76:77], v[28:29] op_sel_hi:[1,0]
	v_pk_mul_f32 v[68:69], v[76:77], v[28:29] op_sel:[0,1]
	v_pk_mul_f32 v[70:71], v[76:77], v[30:31] op_sel_hi:[1,0]
	v_pk_mul_f32 v[72:73], v[76:77], v[30:31] op_sel:[0,1]
	v_pk_fma_f32 v[66:67], v[32:33], v[24:25], v[66:67] op_sel_hi:[1,0,1]
	v_pk_fma_f32 v[68:69], v[32:33], v[24:25], v[68:69] op_sel:[0,1,0]
	v_pk_fma_f32 v[70:71], v[32:33], v[26:27], v[70:71] op_sel_hi:[1,0,1]
	v_pk_fma_f32 v[72:73], v[32:33], v[26:27], v[72:73] op_sel:[0,1,0]
	v_pk_fma_f32 v[0:1], v[0:1], v[20:21], v[66:67] op_sel_hi:[1,0,1]
	v_pk_fma_f32 v[2:3], v[2:3], v[20:21], v[68:69] op_sel:[0,1,0]
	v_pk_fma_f32 v[4:5], v[4:5], v[22:23], v[70:71] op_sel_hi:[1,0,1]
	v_pk_fma_f32 v[6:7], v[6:7], v[22:23], v[72:73] op_sel:[0,1,0]
	ds_write_b32 v84, v36 offset:1280
	ds_write_b32 v84, v76 offset:13568
	s_waitcnt lgkmcnt(7)
	v_pk_mul_f32 v[8:9], v[0:1], v[40:41] op_sel_hi:[1,0]
	v_pk_mul_f32 v[10:11], v[0:1], v[44:45] op_sel_hi:[1,0]
	ds_read_b128 v[12:15], v80 offset:19200
	v_pk_fma_f32 v[8:9], v[2:3], v[40:41], v[8:9] op_sel:[0,1,0]
	v_pk_fma_f32 v[10:11], v[2:3], v[44:45], v[10:11] op_sel:[0,1,0]
	ds_read_b128 v[16:19], v80 offset:18432
	v_pk_fma_f32 v[8:9], v[4:5], v[42:43], v[8:9] op_sel_hi:[1,0,1]
	v_pk_fma_f32 v[10:11], v[4:5], v[46:47], v[10:11] op_sel_hi:[1,0,1]
	ds_read_b128 v[20:23], v80 offset:18688
	v_pk_fma_f32 v[8:9], v[6:7], v[42:43], v[8:9] op_sel:[0,1,0]
	v_pk_fma_f32 v[10:11], v[6:7], v[46:47], v[10:11] op_sel:[0,1,0]
	ds_read_b128 v[24:27], v80 offset:18944
	v_add_f32_dpp v74, v9, v8 row_ror:8 row_mask:0xf bank_mask:0xf bound_ctrl:1
	v_add_f32_dpp v75, v11, v10 row_ror:8 row_mask:0xf bank_mask:0xf bound_ctrl:1
	ds_read_b128 v[28:31], v80 offset:19456
	v_add_f32_dpp v74, v74, v74 quad_perm:[1,0,3,2] row_mask:0xf bank_mask:0xf bound_ctrl:1
	v_add_f32_dpp v75, v75, v75 quad_perm:[1,0,3,2] row_mask:0xf bank_mask:0xf bound_ctrl:1
	ds_read_b32 v32, v81 offset:19712
	v_add_f32_dpp v74, v74, v74 quad_perm:[2,3,0,1] row_mask:0xf bank_mask:0xf bound_ctrl:1
	v_add_f32_dpp v75, v75, v75 quad_perm:[2,3,0,1] row_mask:0xf bank_mask:0xf bound_ctrl:1
	ds_read_b32 v33, v82 offset:19712
	v_add_f32_dpp v76, v74, v74 row_half_mirror row_mask:0xf bank_mask:0xf bound_ctrl:1
	v_add_f32_dpp v64, v75, v75 row_half_mirror row_mask:0xf bank_mask:0xf bound_ctrl:1
	s_nop 0
	v_mov_b32_dpp v77, v76 row_ror:8 row_mask:0xf bank_mask:0xf bound_ctrl:1
	s_waitcnt lgkmcnt(9)
	v_pk_mul_f32 v[66:67], v[76:77], v[56:57] op_sel_hi:[1,0]
	v_pk_mul_f32 v[68:69], v[76:77], v[56:57] op_sel:[0,1]
	v_pk_mul_f32 v[70:71], v[76:77], v[58:59] op_sel_hi:[1,0]
	v_pk_mul_f32 v[72:73], v[76:77], v[58:59] op_sel:[0,1]
	v_pk_fma_f32 v[66:67], v[60:61], v[52:53], v[66:67] op_sel_hi:[1,0,1]
	v_pk_fma_f32 v[68:69], v[60:61], v[52:53], v[68:69] op_sel:[0,1,0]
	v_pk_fma_f32 v[70:71], v[60:61], v[54:55], v[70:71] op_sel_hi:[1,0,1]
	v_pk_fma_f32 v[72:73], v[60:61], v[54:55], v[72:73] op_sel:[0,1,0]
	v_pk_fma_f32 v[0:1], v[0:1], v[48:49], v[66:67] op_sel_hi:[1,0,1]
	v_pk_fma_f32 v[2:3], v[2:3], v[48:49], v[68:69] op_sel:[0,1,0]
	v_pk_fma_f32 v[4:5], v[4:5], v[50:51], v[70:71] op_sel_hi:[1,0,1]
	v_pk_fma_f32 v[6:7], v[6:7], v[50:51], v[72:73] op_sel:[0,1,0]
	ds_write_b32 v84, v64 offset:1408
	ds_write_b32 v84, v76 offset:13696
	s_waitcnt lgkmcnt(7)
	v_pk_mul_f32 v[8:9], v[0:1], v[12:13] op_sel_hi:[1,0]
	v_pk_mul_f32 v[10:11], v[0:1], v[16:17] op_sel_hi:[1,0]
	ds_read_b128 v[40:43], v80 offset:20736
	v_pk_fma_f32 v[8:9], v[2:3], v[12:13], v[8:9] op_sel:[0,1,0]
	v_pk_fma_f32 v[10:11], v[2:3], v[16:17], v[10:11] op_sel:[0,1,0]
	ds_read_b128 v[44:47], v80 offset:19968
	v_pk_fma_f32 v[8:9], v[4:5], v[14:15], v[8:9] op_sel_hi:[1,0,1]
	v_pk_fma_f32 v[10:11], v[4:5], v[18:19], v[10:11] op_sel_hi:[1,0,1]
	ds_read_b128 v[48:51], v80 offset:20224
	v_pk_fma_f32 v[8:9], v[6:7], v[14:15], v[8:9] op_sel:[0,1,0]
	v_pk_fma_f32 v[10:11], v[6:7], v[18:19], v[10:11] op_sel:[0,1,0]
	ds_read_b128 v[52:55], v80 offset:20480
	v_add_f32_dpp v74, v9, v8 row_ror:8 row_mask:0xf bank_mask:0xf bound_ctrl:1
	v_add_f32_dpp v75, v11, v10 row_ror:8 row_mask:0xf bank_mask:0xf bound_ctrl:1
	ds_read_b128 v[56:59], v80 offset:20992
	v_add_f32_dpp v74, v74, v74 quad_perm:[1,0,3,2] row_mask:0xf bank_mask:0xf bound_ctrl:1
	v_add_f32_dpp v75, v75, v75 quad_perm:[1,0,3,2] row_mask:0xf bank_mask:0xf bound_ctrl:1
	ds_read_b32 v60, v81 offset:21248
	v_add_f32_dpp v74, v74, v74 quad_perm:[2,3,0,1] row_mask:0xf bank_mask:0xf bound_ctrl:1
	v_add_f32_dpp v75, v75, v75 quad_perm:[2,3,0,1] row_mask:0xf bank_mask:0xf bound_ctrl:1
	ds_read_b32 v61, v82 offset:21248
	v_add_f32_dpp v76, v74, v74 row_half_mirror row_mask:0xf bank_mask:0xf bound_ctrl:1
	v_add_f32_dpp v36, v75, v75 row_half_mirror row_mask:0xf bank_mask:0xf bound_ctrl:1
	s_nop 0
	v_mov_b32_dpp v77, v76 row_ror:8 row_mask:0xf bank_mask:0xf bound_ctrl:1
	s_waitcnt lgkmcnt(9)
	v_pk_mul_f32 v[66:67], v[76:77], v[28:29] op_sel_hi:[1,0]
	v_pk_mul_f32 v[68:69], v[76:77], v[28:29] op_sel:[0,1]
	v_pk_mul_f32 v[70:71], v[76:77], v[30:31] op_sel_hi:[1,0]
	v_pk_mul_f32 v[72:73], v[76:77], v[30:31] op_sel:[0,1]
	v_pk_fma_f32 v[66:67], v[32:33], v[24:25], v[66:67] op_sel_hi:[1,0,1]
	v_pk_fma_f32 v[68:69], v[32:33], v[24:25], v[68:69] op_sel:[0,1,0]
	v_pk_fma_f32 v[70:71], v[32:33], v[26:27], v[70:71] op_sel_hi:[1,0,1]
	v_pk_fma_f32 v[72:73], v[32:33], v[26:27], v[72:73] op_sel:[0,1,0]
	v_pk_fma_f32 v[0:1], v[0:1], v[20:21], v[66:67] op_sel_hi:[1,0,1]
	v_pk_fma_f32 v[2:3], v[2:3], v[20:21], v[68:69] op_sel:[0,1,0]
	v_pk_fma_f32 v[4:5], v[4:5], v[22:23], v[70:71] op_sel_hi:[1,0,1]
	v_pk_fma_f32 v[6:7], v[6:7], v[22:23], v[72:73] op_sel:[0,1,0]
	ds_write_b32 v84, v36 offset:1536
	ds_write_b32 v84, v76 offset:13824
	s_waitcnt lgkmcnt(7)
	v_pk_mul_f32 v[8:9], v[0:1], v[40:41] op_sel_hi:[1,0]
	v_pk_mul_f32 v[10:11], v[0:1], v[44:45] op_sel_hi:[1,0]
	ds_read_b128 v[12:15], v80 offset:22272
	v_pk_fma_f32 v[8:9], v[2:3], v[40:41], v[8:9] op_sel:[0,1,0]
	v_pk_fma_f32 v[10:11], v[2:3], v[44:45], v[10:11] op_sel:[0,1,0]
	ds_read_b128 v[16:19], v80 offset:21504
	v_pk_fma_f32 v[8:9], v[4:5], v[42:43], v[8:9] op_sel_hi:[1,0,1]
	v_pk_fma_f32 v[10:11], v[4:5], v[46:47], v[10:11] op_sel_hi:[1,0,1]
	ds_read_b128 v[20:23], v80 offset:21760
	v_pk_fma_f32 v[8:9], v[6:7], v[42:43], v[8:9] op_sel:[0,1,0]
	v_pk_fma_f32 v[10:11], v[6:7], v[46:47], v[10:11] op_sel:[0,1,0]
	ds_read_b128 v[24:27], v80 offset:22016
	v_add_f32_dpp v74, v9, v8 row_ror:8 row_mask:0xf bank_mask:0xf bound_ctrl:1
	v_add_f32_dpp v75, v11, v10 row_ror:8 row_mask:0xf bank_mask:0xf bound_ctrl:1
	ds_read_b128 v[28:31], v80 offset:22528
	v_add_f32_dpp v74, v74, v74 quad_perm:[1,0,3,2] row_mask:0xf bank_mask:0xf bound_ctrl:1
	v_add_f32_dpp v75, v75, v75 quad_perm:[1,0,3,2] row_mask:0xf bank_mask:0xf bound_ctrl:1
	ds_read_b32 v32, v81 offset:22784
	v_add_f32_dpp v74, v74, v74 quad_perm:[2,3,0,1] row_mask:0xf bank_mask:0xf bound_ctrl:1
	v_add_f32_dpp v75, v75, v75 quad_perm:[2,3,0,1] row_mask:0xf bank_mask:0xf bound_ctrl:1
	ds_read_b32 v33, v82 offset:22784
	v_add_f32_dpp v76, v74, v74 row_half_mirror row_mask:0xf bank_mask:0xf bound_ctrl:1
	v_add_f32_dpp v64, v75, v75 row_half_mirror row_mask:0xf bank_mask:0xf bound_ctrl:1
	s_nop 0
	v_mov_b32_dpp v77, v76 row_ror:8 row_mask:0xf bank_mask:0xf bound_ctrl:1
	s_waitcnt lgkmcnt(9)
	v_pk_mul_f32 v[66:67], v[76:77], v[56:57] op_sel_hi:[1,0]
	v_pk_mul_f32 v[68:69], v[76:77], v[56:57] op_sel:[0,1]
	v_pk_mul_f32 v[70:71], v[76:77], v[58:59] op_sel_hi:[1,0]
	v_pk_mul_f32 v[72:73], v[76:77], v[58:59] op_sel:[0,1]
	v_pk_fma_f32 v[66:67], v[60:61], v[52:53], v[66:67] op_sel_hi:[1,0,1]
	v_pk_fma_f32 v[68:69], v[60:61], v[52:53], v[68:69] op_sel:[0,1,0]
	v_pk_fma_f32 v[70:71], v[60:61], v[54:55], v[70:71] op_sel_hi:[1,0,1]
	v_pk_fma_f32 v[72:73], v[60:61], v[54:55], v[72:73] op_sel:[0,1,0]
	v_pk_fma_f32 v[0:1], v[0:1], v[48:49], v[66:67] op_sel_hi:[1,0,1]
	v_pk_fma_f32 v[2:3], v[2:3], v[48:49], v[68:69] op_sel:[0,1,0]
	v_pk_fma_f32 v[4:5], v[4:5], v[50:51], v[70:71] op_sel_hi:[1,0,1]
	v_pk_fma_f32 v[6:7], v[6:7], v[50:51], v[72:73] op_sel:[0,1,0]
	ds_write_b32 v84, v64 offset:1664
	ds_write_b32 v84, v76 offset:13952
	s_waitcnt lgkmcnt(7)
	v_pk_mul_f32 v[8:9], v[0:1], v[12:13] op_sel_hi:[1,0]
	v_pk_mul_f32 v[10:11], v[0:1], v[16:17] op_sel_hi:[1,0]
	ds_read_b128 v[40:43], v80 offset:23808
	v_pk_fma_f32 v[8:9], v[2:3], v[12:13], v[8:9] op_sel:[0,1,0]
	v_pk_fma_f32 v[10:11], v[2:3], v[16:17], v[10:11] op_sel:[0,1,0]
	ds_read_b128 v[44:47], v80 offset:23040
	v_pk_fma_f32 v[8:9], v[4:5], v[14:15], v[8:9] op_sel_hi:[1,0,1]
	v_pk_fma_f32 v[10:11], v[4:5], v[18:19], v[10:11] op_sel_hi:[1,0,1]
	ds_read_b128 v[48:51], v80 offset:23296
	v_pk_fma_f32 v[8:9], v[6:7], v[14:15], v[8:9] op_sel:[0,1,0]
	v_pk_fma_f32 v[10:11], v[6:7], v[18:19], v[10:11] op_sel:[0,1,0]
	ds_read_b128 v[52:55], v80 offset:23552
	v_add_f32_dpp v74, v9, v8 row_ror:8 row_mask:0xf bank_mask:0xf bound_ctrl:1
	v_add_f32_dpp v75, v11, v10 row_ror:8 row_mask:0xf bank_mask:0xf bound_ctrl:1
	ds_read_b128 v[56:59], v80 offset:24064
	v_add_f32_dpp v74, v74, v74 quad_perm:[1,0,3,2] row_mask:0xf bank_mask:0xf bound_ctrl:1
	v_add_f32_dpp v75, v75, v75 quad_perm:[1,0,3,2] row_mask:0xf bank_mask:0xf bound_ctrl:1
	ds_read_b32 v60, v81 offset:24320
	v_add_f32_dpp v74, v74, v74 quad_perm:[2,3,0,1] row_mask:0xf bank_mask:0xf bound_ctrl:1
	v_add_f32_dpp v75, v75, v75 quad_perm:[2,3,0,1] row_mask:0xf bank_mask:0xf bound_ctrl:1
	ds_read_b32 v61, v82 offset:24320
	v_add_f32_dpp v76, v74, v74 row_half_mirror row_mask:0xf bank_mask:0xf bound_ctrl:1
	v_add_f32_dpp v36, v75, v75 row_half_mirror row_mask:0xf bank_mask:0xf bound_ctrl:1
	s_nop 0
	v_mov_b32_dpp v77, v76 row_ror:8 row_mask:0xf bank_mask:0xf bound_ctrl:1
	s_waitcnt lgkmcnt(9)
	v_pk_mul_f32 v[66:67], v[76:77], v[28:29] op_sel_hi:[1,0]
	v_pk_mul_f32 v[68:69], v[76:77], v[28:29] op_sel:[0,1]
	v_pk_mul_f32 v[70:71], v[76:77], v[30:31] op_sel_hi:[1,0]
	v_pk_mul_f32 v[72:73], v[76:77], v[30:31] op_sel:[0,1]
	v_pk_fma_f32 v[66:67], v[32:33], v[24:25], v[66:67] op_sel_hi:[1,0,1]
	v_pk_fma_f32 v[68:69], v[32:33], v[24:25], v[68:69] op_sel:[0,1,0]
	v_pk_fma_f32 v[70:71], v[32:33], v[26:27], v[70:71] op_sel_hi:[1,0,1]
	v_pk_fma_f32 v[72:73], v[32:33], v[26:27], v[72:73] op_sel:[0,1,0]
	v_pk_fma_f32 v[0:1], v[0:1], v[20:21], v[66:67] op_sel_hi:[1,0,1]
	v_pk_fma_f32 v[2:3], v[2:3], v[20:21], v[68:69] op_sel:[0,1,0]
	v_pk_fma_f32 v[4:5], v[4:5], v[22:23], v[70:71] op_sel_hi:[1,0,1]
	v_pk_fma_f32 v[6:7], v[6:7], v[22:23], v[72:73] op_sel:[0,1,0]
	ds_write_b32 v84, v36 offset:1792
	ds_write_b32 v84, v76 offset:14080
	s_waitcnt lgkmcnt(7)
	v_pk_mul_f32 v[8:9], v[0:1], v[40:41] op_sel_hi:[1,0]
	v_pk_mul_f32 v[10:11], v[0:1], v[44:45] op_sel_hi:[1,0]
	ds_read_b128 v[12:15], v80 offset:25344
	v_pk_fma_f32 v[8:9], v[2:3], v[40:41], v[8:9] op_sel:[0,1,0]
	v_pk_fma_f32 v[10:11], v[2:3], v[44:45], v[10:11] op_sel:[0,1,0]
	ds_read_b128 v[16:19], v80 offset:24576
	v_pk_fma_f32 v[8:9], v[4:5], v[42:43], v[8:9] op_sel_hi:[1,0,1]
	v_pk_fma_f32 v[10:11], v[4:5], v[46:47], v[10:11] op_sel_hi:[1,0,1]
	ds_read_b128 v[20:23], v80 offset:24832
	v_pk_fma_f32 v[8:9], v[6:7], v[42:43], v[8:9] op_sel:[0,1,0]
	v_pk_fma_f32 v[10:11], v[6:7], v[46:47], v[10:11] op_sel:[0,1,0]
	ds_read_b128 v[24:27], v80 offset:25088
	v_add_f32_dpp v74, v9, v8 row_ror:8 row_mask:0xf bank_mask:0xf bound_ctrl:1
	v_add_f32_dpp v75, v11, v10 row_ror:8 row_mask:0xf bank_mask:0xf bound_ctrl:1
	ds_read_b128 v[28:31], v80 offset:25600
	v_add_f32_dpp v74, v74, v74 quad_perm:[1,0,3,2] row_mask:0xf bank_mask:0xf bound_ctrl:1
	v_add_f32_dpp v75, v75, v75 quad_perm:[1,0,3,2] row_mask:0xf bank_mask:0xf bound_ctrl:1
	ds_read_b32 v32, v81 offset:25856
	v_add_f32_dpp v74, v74, v74 quad_perm:[2,3,0,1] row_mask:0xf bank_mask:0xf bound_ctrl:1
	v_add_f32_dpp v75, v75, v75 quad_perm:[2,3,0,1] row_mask:0xf bank_mask:0xf bound_ctrl:1
	ds_read_b32 v33, v82 offset:25856
	v_add_f32_dpp v76, v74, v74 row_half_mirror row_mask:0xf bank_mask:0xf bound_ctrl:1
	v_add_f32_dpp v64, v75, v75 row_half_mirror row_mask:0xf bank_mask:0xf bound_ctrl:1
	s_nop 0
	v_mov_b32_dpp v77, v76 row_ror:8 row_mask:0xf bank_mask:0xf bound_ctrl:1
	s_waitcnt lgkmcnt(9)
	v_pk_mul_f32 v[66:67], v[76:77], v[56:57] op_sel_hi:[1,0]
	v_pk_mul_f32 v[68:69], v[76:77], v[56:57] op_sel:[0,1]
	v_pk_mul_f32 v[70:71], v[76:77], v[58:59] op_sel_hi:[1,0]
	v_pk_mul_f32 v[72:73], v[76:77], v[58:59] op_sel:[0,1]
	v_pk_fma_f32 v[66:67], v[60:61], v[52:53], v[66:67] op_sel_hi:[1,0,1]
	v_pk_fma_f32 v[68:69], v[60:61], v[52:53], v[68:69] op_sel:[0,1,0]
	v_pk_fma_f32 v[70:71], v[60:61], v[54:55], v[70:71] op_sel_hi:[1,0,1]
	v_pk_fma_f32 v[72:73], v[60:61], v[54:55], v[72:73] op_sel:[0,1,0]
	v_pk_fma_f32 v[0:1], v[0:1], v[48:49], v[66:67] op_sel_hi:[1,0,1]
	v_pk_fma_f32 v[2:3], v[2:3], v[48:49], v[68:69] op_sel:[0,1,0]
	v_pk_fma_f32 v[4:5], v[4:5], v[50:51], v[70:71] op_sel_hi:[1,0,1]
	v_pk_fma_f32 v[6:7], v[6:7], v[50:51], v[72:73] op_sel:[0,1,0]
	ds_write_b32 v84, v64 offset:1920
	ds_write_b32 v84, v76 offset:14208
	s_cmp_eq_u32 s4, 64
	s_cbranch_scc1 .Lrec_chunk_end
	s_waitcnt lgkmcnt(7)
	v_pk_mul_f32 v[8:9], v[0:1], v[12:13] op_sel_hi:[1,0]
	v_pk_mul_f32 v[10:11], v[0:1], v[16:17] op_sel_hi:[1,0]
	ds_read_b128 v[40:43], v80 offset:26880
	v_pk_fma_f32 v[8:9], v[2:3], v[12:13], v[8:9] op_sel:[0,1,0]
	v_pk_fma_f32 v[10:11], v[2:3], v[16:17], v[10:11] op_sel:[0,1,0]
	ds_read_b128 v[44:47], v80 offset:26112
	v_pk_fma_f32 v[8:9], v[4:5], v[14:15], v[8:9] op_sel_hi:[1,0,1]
	v_pk_fma_f32 v[10:11], v[4:5], v[18:19], v[10:11] op_sel_hi:[1,0,1]
	ds_read_b128 v[48:51], v80 offset:26368
	v_pk_fma_f32 v[8:9], v[6:7], v[14:15], v[8:9] op_sel:[0,1,0]
	v_pk_fma_f32 v[10:11], v[6:7], v[18:19], v[10:11] op_sel:[0,1,0]
	ds_read_b128 v[52:55], v80 offset:26624
	v_add_f32_dpp v74, v9, v8 row_ror:8 row_mask:0xf bank_mask:0xf bound_ctrl:1
	v_add_f32_dpp v75, v11, v10 row_ror:8 row_mask:0xf bank_mask:0xf bound_ctrl:1
	ds_read_b128 v[56:59], v80 offset:27136
	v_add_f32_dpp v74, v74, v74 quad_perm:[1,0,3,2] row_mask:0xf bank_mask:0xf bound_ctrl:1
	v_add_f32_dpp v75, v75, v75 quad_perm:[1,0,3,2] row_mask:0xf bank_mask:0xf bound_ctrl:1
	ds_read_b32 v60, v81 offset:27392
	v_add_f32_dpp v74, v74, v74 quad_perm:[2,3,0,1] row_mask:0xf bank_mask:0xf bound_ctrl:1
	v_add_f32_dpp v75, v75, v75 quad_perm:[2,3,0,1] row_mask:0xf bank_mask:0xf bound_ctrl:1
	ds_read_b32 v61, v82 offset:27392
	v_add_f32_dpp v76, v74, v74 row_half_mirror row_mask:0xf bank_mask:0xf bound_ctrl:1
	v_add_f32_dpp v36, v75, v75 row_half_mirror row_mask:0xf bank_mask:0xf bound_ctrl:1
	s_nop 0
	v_mov_b32_dpp v77, v76 row_ror:8 row_mask:0xf bank_mask:0xf bound_ctrl:1
	s_waitcnt lgkmcnt(9)
	v_pk_mul_f32 v[66:67], v[76:77], v[28:29] op_sel_hi:[1,0]
	v_pk_mul_f32 v[68:69], v[76:77], v[28:29] op_sel:[0,1]
	v_pk_mul_f32 v[70:71], v[76:77], v[30:31] op_sel_hi:[1,0]
	v_pk_mul_f32 v[72:73], v[76:77], v[30:31] op_sel:[0,1]
	v_pk_fma_f32 v[66:67], v[32:33], v[24:25], v[66:67] op_sel_hi:[1,0,1]
	v_pk_fma_f32 v[68:69], v[32:33], v[24:25], v[68:69] op_sel:[0,1,0]
	v_pk_fma_f32 v[70:71], v[32:33], v[26:27], v[70:71] op_sel_hi:[1,0,1]
	v_pk_fma_f32 v[72:73], v[32:33], v[26:27], v[72:73] op_sel:[0,1,0]
	v_pk_fma_f32 v[0:1], v[0:1], v[20:21], v[66:67] op_sel_hi:[1,0,1]
	v_pk_fma_f32 v[2:3], v[2:3], v[20:21], v[68:69] op_sel:[0,1,0]
	v_pk_fma_f32 v[4:5], v[4:5], v[22:23], v[70:71] op_sel_hi:[1,0,1]
	v_pk_fma_f32 v[6:7], v[6:7], v[22:23], v[72:73] op_sel:[0,1,0]
	ds_write_b32 v84, v36 offset:2048
	ds_write_b32 v84, v76 offset:14336
	s_waitcnt lgkmcnt(7)
	v_pk_mul_f32 v[8:9], v[0:1], v[40:41] op_sel_hi:[1,0]
	v_pk_mul_f32 v[10:11], v[0:1], v[44:45] op_sel_hi:[1,0]
	ds_read_b128 v[12:15], v80 offset:28416
	v_pk_fma_f32 v[8:9], v[2:3], v[40:41], v[8:9] op_sel:[0,1,0]
	v_pk_fma_f32 v[10:11], v[2:3], v[44:45], v[10:11] op_sel:[0,1,0]
	ds_read_b128 v[16:19], v80 offset:27648
	v_pk_fma_f32 v[8:9], v[4:5], v[42:43], v[8:9] op_sel_hi:[1,0,1]
	v_pk_fma_f32 v[10:11], v[4:5], v[46:47], v[10:11] op_sel_hi:[1,0,1]
	ds_read_b128 v[20:23], v80 offset:27904
	v_pk_fma_f32 v[8:9], v[6:7], v[42:43], v[8:9] op_sel:[0,1,0]
	v_pk_fma_f32 v[10:11], v[6:7], v[46:47], v[10:11] op_sel:[0,1,0]
	ds_read_b128 v[24:27], v80 offset:28160
	v_add_f32_dpp v74, v9, v8 row_ror:8 row_mask:0xf bank_mask:0xf bound_ctrl:1
	v_add_f32_dpp v75, v11, v10 row_ror:8 row_mask:0xf bank_mask:0xf bound_ctrl:1
	ds_read_b128 v[28:31], v80 offset:28672
	v_add_f32_dpp v74, v74, v74 quad_perm:[1,0,3,2] row_mask:0xf bank_mask:0xf bound_ctrl:1
	v_add_f32_dpp v75, v75, v75 quad_perm:[1,0,3,2] row_mask:0xf bank_mask:0xf bound_ctrl:1
	ds_read_b32 v32, v81 offset:28928
	v_add_f32_dpp v74, v74, v74 quad_perm:[2,3,0,1] row_mask:0xf bank_mask:0xf bound_ctrl:1
	v_add_f32_dpp v75, v75, v75 quad_perm:[2,3,0,1] row_mask:0xf bank_mask:0xf bound_ctrl:1
	ds_read_b32 v33, v82 offset:28928
	v_add_f32_dpp v76, v74, v74 row_half_mirror row_mask:0xf bank_mask:0xf bound_ctrl:1
	v_add_f32_dpp v64, v75, v75 row_half_mirror row_mask:0xf bank_mask:0xf bound_ctrl:1
	s_nop 0
	v_mov_b32_dpp v77, v76 row_ror:8 row_mask:0xf bank_mask:0xf bound_ctrl:1
	s_waitcnt lgkmcnt(9)
	v_pk_mul_f32 v[66:67], v[76:77], v[56:57] op_sel_hi:[1,0]
	v_pk_mul_f32 v[68:69], v[76:77], v[56:57] op_sel:[0,1]
	v_pk_mul_f32 v[70:71], v[76:77], v[58:59] op_sel_hi:[1,0]
	v_pk_mul_f32 v[72:73], v[76:77], v[58:59] op_sel:[0,1]
	v_pk_fma_f32 v[66:67], v[60:61], v[52:53], v[66:67] op_sel_hi:[1,0,1]
	v_pk_fma_f32 v[68:69], v[60:61], v[52:53], v[68:69] op_sel:[0,1,0]
	v_pk_fma_f32 v[70:71], v[60:61], v[54:55], v[70:71] op_sel_hi:[1,0,1]
	v_pk_fma_f32 v[72:73], v[60:61], v[54:55], v[72:73] op_sel:[0,1,0]
	v_pk_fma_f32 v[0:1], v[0:1], v[48:49], v[66:67] op_sel_hi:[1,0,1]
	v_pk_fma_f32 v[2:3], v[2:3], v[48:49], v[68:69] op_sel:[0,1,0]
	v_pk_fma_f32 v[4:5], v[4:5], v[50:51], v[70:71] op_sel_hi:[1,0,1]
	v_pk_fma_f32 v[6:7], v[6:7], v[50:51], v[72:73] op_sel:[0,1,0]
	ds_write_b32 v84, v64 offset:2176
	ds_write_b32 v84, v76 offset:14464
	s_waitcnt lgkmcnt(7)
	v_pk_mul_f32 v[8:9], v[0:1], v[12:13] op_sel_hi:[1,0]
	v_pk_mul_f32 v[10:11], v[0:1], v[16:17] op_sel_hi:[1,0]
	ds_read_b128 v[40:43], v80 offset:29952
	v_pk_fma_f32 v[8:9], v[2:3], v[12:13], v[8:9] op_sel:[0,1,0]
	v_pk_fma_f32 v[10:11], v[2:3], v[16:17], v[10:11] op_sel:[0,1,0]
	ds_read_b128 v[44:47], v80 offset:29184
	v_pk_fma_f32 v[8:9], v[4:5], v[14:15], v[8:9] op_sel_hi:[1,0,1]
	v_pk_fma_f32 v[10:11], v[4:5], v[18:19], v[10:11] op_sel_hi:[1,0,1]
	ds_read_b128 v[48:51], v80 offset:29440
	v_pk_fma_f32 v[8:9], v[6:7], v[14:15], v[8:9] op_sel:[0,1,0]
	v_pk_fma_f32 v[10:11], v[6:7], v[18:19], v[10:11] op_sel:[0,1,0]
	ds_read_b128 v[52:55], v80 offset:29696
	v_add_f32_dpp v74, v9, v8 row_ror:8 row_mask:0xf bank_mask:0xf bound_ctrl:1
	v_add_f32_dpp v75, v11, v10 row_ror:8 row_mask:0xf bank_mask:0xf bound_ctrl:1
	ds_read_b128 v[56:59], v80 offset:30208
	v_add_f32_dpp v74, v74, v74 quad_perm:[1,0,3,2] row_mask:0xf bank_mask:0xf bound_ctrl:1
	v_add_f32_dpp v75, v75, v75 quad_perm:[1,0,3,2] row_mask:0xf bank_mask:0xf bound_ctrl:1
	ds_read_b32 v60, v81 offset:30464
	v_add_f32_dpp v74, v74, v74 quad_perm:[2,3,0,1] row_mask:0xf bank_mask:0xf bound_ctrl:1
	v_add_f32_dpp v75, v75, v75 quad_perm:[2,3,0,1] row_mask:0xf bank_mask:0xf bound_ctrl:1
	ds_read_b32 v61, v82 offset:30464
	v_add_f32_dpp v76, v74, v74 row_half_mirror row_mask:0xf bank_mask:0xf bound_ctrl:1
	v_add_f32_dpp v36, v75, v75 row_half_mirror row_mask:0xf bank_mask:0xf bound_ctrl:1
	s_nop 0
	v_mov_b32_dpp v77, v76 row_ror:8 row_mask:0xf bank_mask:0xf bound_ctrl:1
	s_waitcnt lgkmcnt(9)
	v_pk_mul_f32 v[66:67], v[76:77], v[28:29] op_sel_hi:[1,0]
	v_pk_mul_f32 v[68:69], v[76:77], v[28:29] op_sel:[0,1]
	v_pk_mul_f32 v[70:71], v[76:77], v[30:31] op_sel_hi:[1,0]
	v_pk_mul_f32 v[72:73], v[76:77], v[30:31] op_sel:[0,1]
	v_pk_fma_f32 v[66:67], v[32:33], v[24:25], v[66:67] op_sel_hi:[1,0,1]
	v_pk_fma_f32 v[68:69], v[32:33], v[24:25], v[68:69] op_sel:[0,1,0]
	v_pk_fma_f32 v[70:71], v[32:33], v[26:27], v[70:71] op_sel_hi:[1,0,1]
	v_pk_fma_f32 v[72:73], v[32:33], v[26:27], v[72:73] op_sel:[0,1,0]
	v_pk_fma_f32 v[0:1], v[0:1], v[20:21], v[66:67] op_sel_hi:[1,0,1]
	v_pk_fma_f32 v[2:3], v[2:3], v[20:21], v[68:69] op_sel:[0,1,0]
	v_pk_fma_f32 v[4:5], v[4:5], v[22:23], v[70:71] op_sel_hi:[1,0,1]
	v_pk_fma_f32 v[6:7], v[6:7], v[22:23], v[72:73] op_sel:[0,1,0]
	ds_write_b32 v84, v36 offset:2304
	ds_write_b32 v84, v76 offset:14592
	s_waitcnt lgkmcnt(7)
	v_pk_mul_f32 v[8:9], v[0:1], v[40:41] op_sel_hi:[1,0]
	v_pk_mul_f32 v[10:11], v[0:1], v[44:45] op_sel_hi:[1,0]
	ds_read_b128 v[12:15], v80 offset:31488
	v_pk_fma_f32 v[8:9], v[2:3], v[40:41], v[8:9] op_sel:[0,1,0]
	v_pk_fma_f32 v[10:11], v[2:3], v[44:45], v[10:11] op_sel:[0,1,0]
	ds_read_b128 v[16:19], v80 offset:30720
	v_pk_fma_f32 v[8:9], v[4:5], v[42:43], v[8:9] op_sel_hi:[1,0,1]
	v_pk_fma_f32 v[10:11], v[4:5], v[46:47], v[10:11] op_sel_hi:[1,0,1]
	ds_read_b128 v[20:23], v80 offset:30976
	v_pk_fma_f32 v[8:9], v[6:7], v[42:43], v[8:9] op_sel:[0,1,0]
	v_pk_fma_f32 v[10:11], v[6:7], v[46:47], v[10:11] op_sel:[0,1,0]
	ds_read_b128 v[24:27], v80 offset:31232
	v_add_f32_dpp v74, v9, v8 row_ror:8 row_mask:0xf bank_mask:0xf bound_ctrl:1
	v_add_f32_dpp v75, v11, v10 row_ror:8 row_mask:0xf bank_mask:0xf bound_ctrl:1
	ds_read_b128 v[28:31], v80 offset:31744
	v_add_f32_dpp v74, v74, v74 quad_perm:[1,0,3,2] row_mask:0xf bank_mask:0xf bound_ctrl:1
	v_add_f32_dpp v75, v75, v75 quad_perm:[1,0,3,2] row_mask:0xf bank_mask:0xf bound_ctrl:1
	ds_read_b32 v32, v81 offset:32000
	v_add_f32_dpp v74, v74, v74 quad_perm:[2,3,0,1] row_mask:0xf bank_mask:0xf bound_ctrl:1
	v_add_f32_dpp v75, v75, v75 quad_perm:[2,3,0,1] row_mask:0xf bank_mask:0xf bound_ctrl:1
	ds_read_b32 v33, v82 offset:32000
	v_add_f32_dpp v76, v74, v74 row_half_mirror row_mask:0xf bank_mask:0xf bound_ctrl:1
	v_add_f32_dpp v64, v75, v75 row_half_mirror row_mask:0xf bank_mask:0xf bound_ctrl:1
	s_nop 0
	v_mov_b32_dpp v77, v76 row_ror:8 row_mask:0xf bank_mask:0xf bound_ctrl:1
	s_waitcnt lgkmcnt(9)
	v_pk_mul_f32 v[66:67], v[76:77], v[56:57] op_sel_hi:[1,0]
	v_pk_mul_f32 v[68:69], v[76:77], v[56:57] op_sel:[0,1]
	v_pk_mul_f32 v[70:71], v[76:77], v[58:59] op_sel_hi:[1,0]
	v_pk_mul_f32 v[72:73], v[76:77], v[58:59] op_sel:[0,1]
	v_pk_fma_f32 v[66:67], v[60:61], v[52:53], v[66:67] op_sel_hi:[1,0,1]
	v_pk_fma_f32 v[68:69], v[60:61], v[52:53], v[68:69] op_sel:[0,1,0]
	v_pk_fma_f32 v[70:71], v[60:61], v[54:55], v[70:71] op_sel_hi:[1,0,1]
	v_pk_fma_f32 v[72:73], v[60:61], v[54:55], v[72:73] op_sel:[0,1,0]
	v_pk_fma_f32 v[0:1], v[0:1], v[48:49], v[66:67] op_sel_hi:[1,0,1]
	v_pk_fma_f32 v[2:3], v[2:3], v[48:49], v[68:69] op_sel:[0,1,0]
	v_pk_fma_f32 v[4:5], v[4:5], v[50:51], v[70:71] op_sel_hi:[1,0,1]
	v_pk_fma_f32 v[6:7], v[6:7], v[50:51], v[72:73] op_sel:[0,1,0]
	ds_write_b32 v84, v64 offset:2432
	ds_write_b32 v84, v76 offset:14720
	s_waitcnt lgkmcnt(7)
	v_pk_mul_f32 v[8:9], v[0:1], v[12:13] op_sel_hi:[1,0]
	v_pk_mul_f32 v[10:11], v[0:1], v[16:17] op_sel_hi:[1,0]
	ds_read_b128 v[40:43], v80 offset:33024
	v_pk_fma_f32 v[8:9], v[2:3], v[12:13], v[8:9] op_sel:[0,1,0]
	v_pk_fma_f32 v[10:11], v[2:3], v[16:17], v[10:11] op_sel:[0,1,0]
	ds_read_b128 v[44:47], v80 offset:32256
	v_pk_fma_f32 v[8:9], v[4:5], v[14:15], v[8:9] op_sel_hi:[1,0,1]
	v_pk_fma_f32 v[10:11], v[4:5], v[18:19], v[10:11] op_sel_hi:[1,0,1]
	ds_read_b128 v[48:51], v80 offset:32512
	v_pk_fma_f32 v[8:9], v[6:7], v[14:15], v[8:9] op_sel:[0,1,0]
	v_pk_fma_f32 v[10:11], v[6:7], v[18:19], v[10:11] op_sel:[0,1,0]
	ds_read_b128 v[52:55], v80 offset:32768
	v_add_f32_dpp v74, v9, v8 row_ror:8 row_mask:0xf bank_mask:0xf bound_ctrl:1
	v_add_f32_dpp v75, v11, v10 row_ror:8 row_mask:0xf bank_mask:0xf bound_ctrl:1
	ds_read_b128 v[56:59], v80 offset:33280
	v_add_f32_dpp v74, v74, v74 quad_perm:[1,0,3,2] row_mask:0xf bank_mask:0xf bound_ctrl:1
	v_add_f32_dpp v75, v75, v75 quad_perm:[1,0,3,2] row_mask:0xf bank_mask:0xf bound_ctrl:1
	ds_read_b32 v60, v81 offset:33536
	v_add_f32_dpp v74, v74, v74 quad_perm:[2,3,0,1] row_mask:0xf bank_mask:0xf bound_ctrl:1
	v_add_f32_dpp v75, v75, v75 quad_perm:[2,3,0,1] row_mask:0xf bank_mask:0xf bound_ctrl:1
	ds_read_b32 v61, v82 offset:33536
	v_add_f32_dpp v76, v74, v74 row_half_mirror row_mask:0xf bank_mask:0xf bound_ctrl:1
	v_add_f32_dpp v36, v75, v75 row_half_mirror row_mask:0xf bank_mask:0xf bound_ctrl:1
	s_nop 0
	v_mov_b32_dpp v77, v76 row_ror:8 row_mask:0xf bank_mask:0xf bound_ctrl:1
	s_waitcnt lgkmcnt(9)
	v_pk_mul_f32 v[66:67], v[76:77], v[28:29] op_sel_hi:[1,0]
	v_pk_mul_f32 v[68:69], v[76:77], v[28:29] op_sel:[0,1]
	v_pk_mul_f32 v[70:71], v[76:77], v[30:31] op_sel_hi:[1,0]
	v_pk_mul_f32 v[72:73], v[76:77], v[30:31] op_sel:[0,1]
	v_pk_fma_f32 v[66:67], v[32:33], v[24:25], v[66:67] op_sel_hi:[1,0,1]
	v_pk_fma_f32 v[68:69], v[32:33], v[24:25], v[68:69] op_sel:[0,1,0]
	v_pk_fma_f32 v[70:71], v[32:33], v[26:27], v[70:71] op_sel_hi:[1,0,1]
	v_pk_fma_f32 v[72:73], v[32:33], v[26:27], v[72:73] op_sel:[0,1,0]
	v_pk_fma_f32 v[0:1], v[0:1], v[20:21], v[66:67] op_sel_hi:[1,0,1]
	v_pk_fma_f32 v[2:3], v[2:3], v[20:21], v[68:69] op_sel:[0,1,0]
	v_pk_fma_f32 v[4:5], v[4:5], v[22:23], v[70:71] op_sel_hi:[1,0,1]
	v_pk_fma_f32 v[6:7], v[6:7], v[22:23], v[72:73] op_sel:[0,1,0]
	ds_write_b32 v84, v36 offset:2560
	ds_write_b32 v84, v76 offset:14848
	s_waitcnt lgkmcnt(7)
	v_pk_mul_f32 v[8:9], v[0:1], v[40:41] op_sel_hi:[1,0]
	v_pk_mul_f32 v[10:11], v[0:1], v[44:45] op_sel_hi:[1,0]
	ds_read_b128 v[12:15], v80 offset:34560
	v_pk_fma_f32 v[8:9], v[2:3], v[40:41], v[8:9] op_sel:[0,1,0]
	v_pk_fma_f32 v[10:11], v[2:3], v[44:45], v[10:11] op_sel:[0,1,0]
	ds_read_b128 v[16:19], v80 offset:33792
	v_pk_fma_f32 v[8:9], v[4:5], v[42:43], v[8:9] op_sel_hi:[1,0,1]
	v_pk_fma_f32 v[10:11], v[4:5], v[46:47], v[10:11] op_sel_hi:[1,0,1]
	ds_read_b128 v[20:23], v80 offset:34048
	v_pk_fma_f32 v[8:9], v[6:7], v[42:43], v[8:9] op_sel:[0,1,0]
	v_pk_fma_f32 v[10:11], v[6:7], v[46:47], v[10:11] op_sel:[0,1,0]
	ds_read_b128 v[24:27], v80 offset:34304
	v_add_f32_dpp v74, v9, v8 row_ror:8 row_mask:0xf bank_mask:0xf bound_ctrl:1
	v_add_f32_dpp v75, v11, v10 row_ror:8 row_mask:0xf bank_mask:0xf bound_ctrl:1
	ds_read_b128 v[28:31], v80 offset:34816
	v_add_f32_dpp v74, v74, v74 quad_perm:[1,0,3,2] row_mask:0xf bank_mask:0xf bound_ctrl:1
	v_add_f32_dpp v75, v75, v75 quad_perm:[1,0,3,2] row_mask:0xf bank_mask:0xf bound_ctrl:1
	ds_read_b32 v32, v81 offset:35072
	v_add_f32_dpp v74, v74, v74 quad_perm:[2,3,0,1] row_mask:0xf bank_mask:0xf bound_ctrl:1
	v_add_f32_dpp v75, v75, v75 quad_perm:[2,3,0,1] row_mask:0xf bank_mask:0xf bound_ctrl:1
	ds_read_b32 v33, v82 offset:35072
	v_add_f32_dpp v76, v74, v74 row_half_mirror row_mask:0xf bank_mask:0xf bound_ctrl:1
	v_add_f32_dpp v64, v75, v75 row_half_mirror row_mask:0xf bank_mask:0xf bound_ctrl:1
	s_nop 0
	v_mov_b32_dpp v77, v76 row_ror:8 row_mask:0xf bank_mask:0xf bound_ctrl:1
	s_waitcnt lgkmcnt(9)
	v_pk_mul_f32 v[66:67], v[76:77], v[56:57] op_sel_hi:[1,0]
	v_pk_mul_f32 v[68:69], v[76:77], v[56:57] op_sel:[0,1]
	v_pk_mul_f32 v[70:71], v[76:77], v[58:59] op_sel_hi:[1,0]
	v_pk_mul_f32 v[72:73], v[76:77], v[58:59] op_sel:[0,1]
	v_pk_fma_f32 v[66:67], v[60:61], v[52:53], v[66:67] op_sel_hi:[1,0,1]
	v_pk_fma_f32 v[68:69], v[60:61], v[52:53], v[68:69] op_sel:[0,1,0]
	v_pk_fma_f32 v[70:71], v[60:61], v[54:55], v[70:71] op_sel_hi:[1,0,1]
	v_pk_fma_f32 v[72:73], v[60:61], v[54:55], v[72:73] op_sel:[0,1,0]
	v_pk_fma_f32 v[0:1], v[0:1], v[48:49], v[66:67] op_sel_hi:[1,0,1]
	v_pk_fma_f32 v[2:3], v[2:3], v[48:49], v[68:69] op_sel:[0,1,0]
	v_pk_fma_f32 v[4:5], v[4:5], v[50:51], v[70:71] op_sel_hi:[1,0,1]
	v_pk_fma_f32 v[6:7], v[6:7], v[50:51], v[72:73] op_sel:[0,1,0]
	ds_write_b32 v84, v64 offset:2688
	ds_write_b32 v84, v76 offset:14976
	s_waitcnt lgkmcnt(7)
	v_pk_mul_f32 v[8:9], v[0:1], v[12:13] op_sel_hi:[1,0]
	v_pk_mul_f32 v[10:11], v[0:1], v[16:17] op_sel_hi:[1,0]
	ds_read_b128 v[40:43], v80 offset:36096
	v_pk_fma_f32 v[8:9], v[2:3], v[12:13], v[8:9] op_sel:[0,1,0]
	v_pk_fma_f32 v[10:11], v[2:3], v[16:17], v[10:11] op_sel:[0,1,0]
	ds_read_b128 v[44:47], v80 offset:35328
	v_pk_fma_f32 v[8:9], v[4:5], v[14:15], v[8:9] op_sel_hi:[1,0,1]
	v_pk_fma_f32 v[10:11], v[4:5], v[18:19], v[10:11] op_sel_hi:[1,0,1]
	ds_read_b128 v[48:51], v80 offset:35584
	v_pk_fma_f32 v[8:9], v[6:7], v[14:15], v[8:9] op_sel:[0,1,0]
	v_pk_fma_f32 v[10:11], v[6:7], v[18:19], v[10:11] op_sel:[0,1,0]
	ds_read_b128 v[52:55], v80 offset:35840
	v_add_f32_dpp v74, v9, v8 row_ror:8 row_mask:0xf bank_mask:0xf bound_ctrl:1
	v_add_f32_dpp v75, v11, v10 row_ror:8 row_mask:0xf bank_mask:0xf bound_ctrl:1
	ds_read_b128 v[56:59], v80 offset:36352
	v_add_f32_dpp v74, v74, v74 quad_perm:[1,0,3,2] row_mask:0xf bank_mask:0xf bound_ctrl:1
	v_add_f32_dpp v75, v75, v75 quad_perm:[1,0,3,2] row_mask:0xf bank_mask:0xf bound_ctrl:1
	ds_read_b32 v60, v81 offset:36608
	v_add_f32_dpp v74, v74, v74 quad_perm:[2,3,0,1] row_mask:0xf bank_mask:0xf bound_ctrl:1
	v_add_f32_dpp v75, v75, v75 quad_perm:[2,3,0,1] row_mask:0xf bank_mask:0xf bound_ctrl:1
	ds_read_b32 v61, v82 offset:36608
	v_add_f32_dpp v76, v74, v74 row_half_mirror row_mask:0xf bank_mask:0xf bound_ctrl:1
	v_add_f32_dpp v36, v75, v75 row_half_mirror row_mask:0xf bank_mask:0xf bound_ctrl:1
	s_nop 0
	v_mov_b32_dpp v77, v76 row_ror:8 row_mask:0xf bank_mask:0xf bound_ctrl:1
	s_waitcnt lgkmcnt(9)
	v_pk_mul_f32 v[66:67], v[76:77], v[28:29] op_sel_hi:[1,0]
	v_pk_mul_f32 v[68:69], v[76:77], v[28:29] op_sel:[0,1]
	v_pk_mul_f32 v[70:71], v[76:77], v[30:31] op_sel_hi:[1,0]
	v_pk_mul_f32 v[72:73], v[76:77], v[30:31] op_sel:[0,1]
	v_pk_fma_f32 v[66:67], v[32:33], v[24:25], v[66:67] op_sel_hi:[1,0,1]
	v_pk_fma_f32 v[68:69], v[32:33], v[24:25], v[68:69] op_sel:[0,1,0]
	v_pk_fma_f32 v[70:71], v[32:33], v[26:27], v[70:71] op_sel_hi:[1,0,1]
	v_pk_fma_f32 v[72:73], v[32:33], v[26:27], v[72:73] op_sel:[0,1,0]
	v_pk_fma_f32 v[0:1], v[0:1], v[20:21], v[66:67] op_sel_hi:[1,0,1]
	v_pk_fma_f32 v[2:3], v[2:3], v[20:21], v[68:69] op_sel:[0,1,0]
	v_pk_fma_f32 v[4:5], v[4:5], v[22:23], v[70:71] op_sel_hi:[1,0,1]
	v_pk_fma_f32 v[6:7], v[6:7], v[22:23], v[72:73] op_sel:[0,1,0]
	ds_write_b32 v84, v36 offset:2816
	ds_write_b32 v84, v76 offset:15104
	s_waitcnt lgkmcnt(7)
	v_pk_mul_f32 v[8:9], v[0:1], v[40:41] op_sel_hi:[1,0]
	v_pk_mul_f32 v[10:11], v[0:1], v[44:45] op_sel_hi:[1,0]
	ds_read_b128 v[12:15], v80 offset:37632
	v_pk_fma_f32 v[8:9], v[2:3], v[40:41], v[8:9] op_sel:[0,1,0]
	v_pk_fma_f32 v[10:11], v[2:3], v[44:45], v[10:11] op_sel:[0,1,0]
	ds_read_b128 v[16:19], v80 offset:36864
	v_pk_fma_f32 v[8:9], v[4:5], v[42:43], v[8:9] op_sel_hi:[1,0,1]
	v_pk_fma_f32 v[10:11], v[4:5], v[46:47], v[10:11] op_sel_hi:[1,0,1]
	ds_read_b128 v[20:23], v80 offset:37120
	v_pk_fma_f32 v[8:9], v[6:7], v[42:43], v[8:9] op_sel:[0,1,0]
	v_pk_fma_f32 v[10:11], v[6:7], v[46:47], v[10:11] op_sel:[0,1,0]
	ds_read_b128 v[24:27], v80 offset:37376
	v_add_f32_dpp v74, v9, v8 row_ror:8 row_mask:0xf bank_mask:0xf bound_ctrl:1
	v_add_f32_dpp v75, v11, v10 row_ror:8 row_mask:0xf bank_mask:0xf bound_ctrl:1
	ds_read_b128 v[28:31], v80 offset:37888
	v_add_f32_dpp v74, v74, v74 quad_perm:[1,0,3,2] row_mask:0xf bank_mask:0xf bound_ctrl:1
	v_add_f32_dpp v75, v75, v75 quad_perm:[1,0,3,2] row_mask:0xf bank_mask:0xf bound_ctrl:1
	ds_read_b32 v32, v81 offset:38144
	v_add_f32_dpp v74, v74, v74 quad_perm:[2,3,0,1] row_mask:0xf bank_mask:0xf bound_ctrl:1
	v_add_f32_dpp v75, v75, v75 quad_perm:[2,3,0,1] row_mask:0xf bank_mask:0xf bound_ctrl:1
	ds_read_b32 v33, v82 offset:38144
	v_add_f32_dpp v76, v74, v74 row_half_mirror row_mask:0xf bank_mask:0xf bound_ctrl:1
	v_add_f32_dpp v64, v75, v75 row_half_mirror row_mask:0xf bank_mask:0xf bound_ctrl:1
	s_nop 0
	v_mov_b32_dpp v77, v76 row_ror:8 row_mask:0xf bank_mask:0xf bound_ctrl:1
	s_waitcnt lgkmcnt(9)
	v_pk_mul_f32 v[66:67], v[76:77], v[56:57] op_sel_hi:[1,0]
	v_pk_mul_f32 v[68:69], v[76:77], v[56:57] op_sel:[0,1]
	v_pk_mul_f32 v[70:71], v[76:77], v[58:59] op_sel_hi:[1,0]
	v_pk_mul_f32 v[72:73], v[76:77], v[58:59] op_sel:[0,1]
	v_pk_fma_f32 v[66:67], v[60:61], v[52:53], v[66:67] op_sel_hi:[1,0,1]
	v_pk_fma_f32 v[68:69], v[60:61], v[52:53], v[68:69] op_sel:[0,1,0]
	v_pk_fma_f32 v[70:71], v[60:61], v[54:55], v[70:71] op_sel_hi:[1,0,1]
	v_pk_fma_f32 v[72:73], v[60:61], v[54:55], v[72:73] op_sel:[0,1,0]
	v_pk_fma_f32 v[0:1], v[0:1], v[48:49], v[66:67] op_sel_hi:[1,0,1]
	v_pk_fma_f32 v[2:3], v[2:3], v[48:49], v[68:69] op_sel:[0,1,0]
	v_pk_fma_f32 v[4:5], v[4:5], v[50:51], v[70:71] op_sel_hi:[1,0,1]
	v_pk_fma_f32 v[6:7], v[6:7], v[50:51], v[72:73] op_sel:[0,1,0]
	ds_write_b32 v84, v64 offset:2944
	ds_write_b32 v84, v76 offset:15232
	s_waitcnt lgkmcnt(7)
	v_pk_mul_f32 v[8:9], v[0:1], v[12:13] op_sel_hi:[1,0]
	v_pk_mul_f32 v[10:11], v[0:1], v[16:17] op_sel_hi:[1,0]
	ds_read_b128 v[40:43], v80 offset:39168
	v_pk_fma_f32 v[8:9], v[2:3], v[12:13], v[8:9] op_sel:[0,1,0]
	v_pk_fma_f32 v[10:11], v[2:3], v[16:17], v[10:11] op_sel:[0,1,0]
	ds_read_b128 v[44:47], v80 offset:38400
	v_pk_fma_f32 v[8:9], v[4:5], v[14:15], v[8:9] op_sel_hi:[1,0,1]
	v_pk_fma_f32 v[10:11], v[4:5], v[18:19], v[10:11] op_sel_hi:[1,0,1]
	ds_read_b128 v[48:51], v80 offset:38656
	v_pk_fma_f32 v[8:9], v[6:7], v[14:15], v[8:9] op_sel:[0,1,0]
	v_pk_fma_f32 v[10:11], v[6:7], v[18:19], v[10:11] op_sel:[0,1,0]
	ds_read_b128 v[52:55], v80 offset:38912
	v_add_f32_dpp v74, v9, v8 row_ror:8 row_mask:0xf bank_mask:0xf bound_ctrl:1
	v_add_f32_dpp v75, v11, v10 row_ror:8 row_mask:0xf bank_mask:0xf bound_ctrl:1
	ds_read_b128 v[56:59], v80 offset:39424
	v_add_f32_dpp v74, v74, v74 quad_perm:[1,0,3,2] row_mask:0xf bank_mask:0xf bound_ctrl:1
	v_add_f32_dpp v75, v75, v75 quad_perm:[1,0,3,2] row_mask:0xf bank_mask:0xf bound_ctrl:1
	ds_read_b32 v60, v81 offset:39680
	v_add_f32_dpp v74, v74, v74 quad_perm:[2,3,0,1] row_mask:0xf bank_mask:0xf bound_ctrl:1
	v_add_f32_dpp v75, v75, v75 quad_perm:[2,3,0,1] row_mask:0xf bank_mask:0xf bound_ctrl:1
	ds_read_b32 v61, v82 offset:39680
	v_add_f32_dpp v76, v74, v74 row_half_mirror row_mask:0xf bank_mask:0xf bound_ctrl:1
	v_add_f32_dpp v36, v75, v75 row_half_mirror row_mask:0xf bank_mask:0xf bound_ctrl:1
	s_nop 0
	v_mov_b32_dpp v77, v76 row_ror:8 row_mask:0xf bank_mask:0xf bound_ctrl:1
	s_waitcnt lgkmcnt(9)
	v_pk_mul_f32 v[66:67], v[76:77], v[28:29] op_sel_hi:[1,0]
	v_pk_mul_f32 v[68:69], v[76:77], v[28:29] op_sel:[0,1]
	v_pk_mul_f32 v[70:71], v[76:77], v[30:31] op_sel_hi:[1,0]
	v_pk_mul_f32 v[72:73], v[76:77], v[30:31] op_sel:[0,1]
	v_pk_fma_f32 v[66:67], v[32:33], v[24:25], v[66:67] op_sel_hi:[1,0,1]
	v_pk_fma_f32 v[68:69], v[32:33], v[24:25], v[68:69] op_sel:[0,1,0]
	v_pk_fma_f32 v[70:71], v[32:33], v[26:27], v[70:71] op_sel_hi:[1,0,1]
	v_pk_fma_f32 v[72:73], v[32:33], v[26:27], v[72:73] op_sel:[0,1,0]
	v_pk_fma_f32 v[0:1], v[0:1], v[20:21], v[66:67] op_sel_hi:[1,0,1]
	v_pk_fma_f32 v[2:3], v[2:3], v[20:21], v[68:69] op_sel:[0,1,0]
	v_pk_fma_f32 v[4:5], v[4:5], v[22:23], v[70:71] op_sel_hi:[1,0,1]
	v_pk_fma_f32 v[6:7], v[6:7], v[22:23], v[72:73] op_sel:[0,1,0]
	ds_write_b32 v84, v36 offset:3072
	ds_write_b32 v84, v76 offset:15360
	s_waitcnt lgkmcnt(7)
	v_pk_mul_f32 v[8:9], v[0:1], v[40:41] op_sel_hi:[1,0]
	v_pk_mul_f32 v[10:11], v[0:1], v[44:45] op_sel_hi:[1,0]
	ds_read_b128 v[12:15], v80 offset:40704
	v_pk_fma_f32 v[8:9], v[2:3], v[40:41], v[8:9] op_sel:[0,1,0]
	v_pk_fma_f32 v[10:11], v[2:3], v[44:45], v[10:11] op_sel:[0,1,0]
	ds_read_b128 v[16:19], v80 offset:39936
	v_pk_fma_f32 v[8:9], v[4:5], v[42:43], v[8:9] op_sel_hi:[1,0,1]
	v_pk_fma_f32 v[10:11], v[4:5], v[46:47], v[10:11] op_sel_hi:[1,0,1]
	ds_read_b128 v[20:23], v80 offset:40192
	v_pk_fma_f32 v[8:9], v[6:7], v[42:43], v[8:9] op_sel:[0,1,0]
	v_pk_fma_f32 v[10:11], v[6:7], v[46:47], v[10:11] op_sel:[0,1,0]
	ds_read_b128 v[24:27], v80 offset:40448
	v_add_f32_dpp v74, v9, v8 row_ror:8 row_mask:0xf bank_mask:0xf bound_ctrl:1
	v_add_f32_dpp v75, v11, v10 row_ror:8 row_mask:0xf bank_mask:0xf bound_ctrl:1
	ds_read_b128 v[28:31], v80 offset:40960
	v_add_f32_dpp v74, v74, v74 quad_perm:[1,0,3,2] row_mask:0xf bank_mask:0xf bound_ctrl:1
	v_add_f32_dpp v75, v75, v75 quad_perm:[1,0,3,2] row_mask:0xf bank_mask:0xf bound_ctrl:1
	ds_read_b32 v32, v81 offset:41216
	v_add_f32_dpp v74, v74, v74 quad_perm:[2,3,0,1] row_mask:0xf bank_mask:0xf bound_ctrl:1
	v_add_f32_dpp v75, v75, v75 quad_perm:[2,3,0,1] row_mask:0xf bank_mask:0xf bound_ctrl:1
	ds_read_b32 v33, v82 offset:41216
	v_add_f32_dpp v76, v74, v74 row_half_mirror row_mask:0xf bank_mask:0xf bound_ctrl:1
	v_add_f32_dpp v64, v75, v75 row_half_mirror row_mask:0xf bank_mask:0xf bound_ctrl:1
	s_nop 0
	v_mov_b32_dpp v77, v76 row_ror:8 row_mask:0xf bank_mask:0xf bound_ctrl:1
	s_waitcnt lgkmcnt(9)
	v_pk_mul_f32 v[66:67], v[76:77], v[56:57] op_sel_hi:[1,0]
	v_pk_mul_f32 v[68:69], v[76:77], v[56:57] op_sel:[0,1]
	v_pk_mul_f32 v[70:71], v[76:77], v[58:59] op_sel_hi:[1,0]
	v_pk_mul_f32 v[72:73], v[76:77], v[58:59] op_sel:[0,1]
	v_pk_fma_f32 v[66:67], v[60:61], v[52:53], v[66:67] op_sel_hi:[1,0,1]
	v_pk_fma_f32 v[68:69], v[60:61], v[52:53], v[68:69] op_sel:[0,1,0]
	v_pk_fma_f32 v[70:71], v[60:61], v[54:55], v[70:71] op_sel_hi:[1,0,1]
	v_pk_fma_f32 v[72:73], v[60:61], v[54:55], v[72:73] op_sel:[0,1,0]
	v_pk_fma_f32 v[0:1], v[0:1], v[48:49], v[66:67] op_sel_hi:[1,0,1]
	v_pk_fma_f32 v[2:3], v[2:3], v[48:49], v[68:69] op_sel:[0,1,0]
	v_pk_fma_f32 v[4:5], v[4:5], v[50:51], v[70:71] op_sel_hi:[1,0,1]
	v_pk_fma_f32 v[6:7], v[6:7], v[50:51], v[72:73] op_sel:[0,1,0]
	ds_write_b32 v84, v64 offset:3200
	ds_write_b32 v84, v76 offset:15488
	s_waitcnt lgkmcnt(7)
	v_pk_mul_f32 v[8:9], v[0:1], v[12:13] op_sel_hi:[1,0]
	v_pk_mul_f32 v[10:11], v[0:1], v[16:17] op_sel_hi:[1,0]
	ds_read_b128 v[40:43], v80 offset:42240
	v_pk_fma_f32 v[8:9], v[2:3], v[12:13], v[8:9] op_sel:[0,1,0]
	v_pk_fma_f32 v[10:11], v[2:3], v[16:17], v[10:11] op_sel:[0,1,0]
	ds_read_b128 v[44:47], v80 offset:41472
	v_pk_fma_f32 v[8:9], v[4:5], v[14:15], v[8:9] op_sel_hi:[1,0,1]
	v_pk_fma_f32 v[10:11], v[4:5], v[18:19], v[10:11] op_sel_hi:[1,0,1]
	ds_read_b128 v[48:51], v80 offset:41728
	v_pk_fma_f32 v[8:9], v[6:7], v[14:15], v[8:9] op_sel:[0,1,0]
	v_pk_fma_f32 v[10:11], v[6:7], v[18:19], v[10:11] op_sel:[0,1,0]
	ds_read_b128 v[52:55], v80 offset:41984
	v_add_f32_dpp v74, v9, v8 row_ror:8 row_mask:0xf bank_mask:0xf bound_ctrl:1
	v_add_f32_dpp v75, v11, v10 row_ror:8 row_mask:0xf bank_mask:0xf bound_ctrl:1
	ds_read_b128 v[56:59], v80 offset:42496
	v_add_f32_dpp v74, v74, v74 quad_perm:[1,0,3,2] row_mask:0xf bank_mask:0xf bound_ctrl:1
	v_add_f32_dpp v75, v75, v75 quad_perm:[1,0,3,2] row_mask:0xf bank_mask:0xf bound_ctrl:1
	ds_read_b32 v60, v81 offset:42752
	v_add_f32_dpp v74, v74, v74 quad_perm:[2,3,0,1] row_mask:0xf bank_mask:0xf bound_ctrl:1
	v_add_f32_dpp v75, v75, v75 quad_perm:[2,3,0,1] row_mask:0xf bank_mask:0xf bound_ctrl:1
	ds_read_b32 v61, v82 offset:42752
	v_add_f32_dpp v76, v74, v74 row_half_mirror row_mask:0xf bank_mask:0xf bound_ctrl:1
	v_add_f32_dpp v36, v75, v75 row_half_mirror row_mask:0xf bank_mask:0xf bound_ctrl:1
	s_nop 0
	v_mov_b32_dpp v77, v76 row_ror:8 row_mask:0xf bank_mask:0xf bound_ctrl:1
	s_waitcnt lgkmcnt(9)
	v_pk_mul_f32 v[66:67], v[76:77], v[28:29] op_sel_hi:[1,0]
	v_pk_mul_f32 v[68:69], v[76:77], v[28:29] op_sel:[0,1]
	v_pk_mul_f32 v[70:71], v[76:77], v[30:31] op_sel_hi:[1,0]
	v_pk_mul_f32 v[72:73], v[76:77], v[30:31] op_sel:[0,1]
	v_pk_fma_f32 v[66:67], v[32:33], v[24:25], v[66:67] op_sel_hi:[1,0,1]
	v_pk_fma_f32 v[68:69], v[32:33], v[24:25], v[68:69] op_sel:[0,1,0]
	v_pk_fma_f32 v[70:71], v[32:33], v[26:27], v[70:71] op_sel_hi:[1,0,1]
	v_pk_fma_f32 v[72:73], v[32:33], v[26:27], v[72:73] op_sel:[0,1,0]
	v_pk_fma_f32 v[0:1], v[0:1], v[20:21], v[66:67] op_sel_hi:[1,0,1]
	v_pk_fma_f32 v[2:3], v[2:3], v[20:21], v[68:69] op_sel:[0,1,0]
	v_pk_fma_f32 v[4:5], v[4:5], v[22:23], v[70:71] op_sel_hi:[1,0,1]
	v_pk_fma_f32 v[6:7], v[6:7], v[22:23], v[72:73] op_sel:[0,1,0]
	ds_write_b32 v84, v36 offset:3328
	ds_write_b32 v84, v76 offset:15616
	s_waitcnt lgkmcnt(7)
	v_pk_mul_f32 v[8:9], v[0:1], v[40:41] op_sel_hi:[1,0]
	v_pk_mul_f32 v[10:11], v[0:1], v[44:45] op_sel_hi:[1,0]
	ds_read_b128 v[12:15], v80 offset:43776
	v_pk_fma_f32 v[8:9], v[2:3], v[40:41], v[8:9] op_sel:[0,1,0]
	v_pk_fma_f32 v[10:11], v[2:3], v[44:45], v[10:11] op_sel:[0,1,0]
	ds_read_b128 v[16:19], v80 offset:43008
	v_pk_fma_f32 v[8:9], v[4:5], v[42:43], v[8:9] op_sel_hi:[1,0,1]
	v_pk_fma_f32 v[10:11], v[4:5], v[46:47], v[10:11] op_sel_hi:[1,0,1]
	ds_read_b128 v[20:23], v80 offset:43264
	v_pk_fma_f32 v[8:9], v[6:7], v[42:43], v[8:9] op_sel:[0,1,0]
	v_pk_fma_f32 v[10:11], v[6:7], v[46:47], v[10:11] op_sel:[0,1,0]
	ds_read_b128 v[24:27], v80 offset:43520
	v_add_f32_dpp v74, v9, v8 row_ror:8 row_mask:0xf bank_mask:0xf bound_ctrl:1
	v_add_f32_dpp v75, v11, v10 row_ror:8 row_mask:0xf bank_mask:0xf bound_ctrl:1
	ds_read_b128 v[28:31], v80 offset:44032
	v_add_f32_dpp v74, v74, v74 quad_perm:[1,0,3,2] row_mask:0xf bank_mask:0xf bound_ctrl:1
	v_add_f32_dpp v75, v75, v75 quad_perm:[1,0,3,2] row_mask:0xf bank_mask:0xf bound_ctrl:1
	ds_read_b32 v32, v81 offset:44288
	v_add_f32_dpp v74, v74, v74 quad_perm:[2,3,0,1] row_mask:0xf bank_mask:0xf bound_ctrl:1
	v_add_f32_dpp v75, v75, v75 quad_perm:[2,3,0,1] row_mask:0xf bank_mask:0xf bound_ctrl:1
	ds_read_b32 v33, v82 offset:44288
	v_add_f32_dpp v76, v74, v74 row_half_mirror row_mask:0xf bank_mask:0xf bound_ctrl:1
	v_add_f32_dpp v64, v75, v75 row_half_mirror row_mask:0xf bank_mask:0xf bound_ctrl:1
	s_nop 0
	v_mov_b32_dpp v77, v76 row_ror:8 row_mask:0xf bank_mask:0xf bound_ctrl:1
	s_waitcnt lgkmcnt(9)
	v_pk_mul_f32 v[66:67], v[76:77], v[56:57] op_sel_hi:[1,0]
	v_pk_mul_f32 v[68:69], v[76:77], v[56:57] op_sel:[0,1]
	v_pk_mul_f32 v[70:71], v[76:77], v[58:59] op_sel_hi:[1,0]
	v_pk_mul_f32 v[72:73], v[76:77], v[58:59] op_sel:[0,1]
	v_pk_fma_f32 v[66:67], v[60:61], v[52:53], v[66:67] op_sel_hi:[1,0,1]
	v_pk_fma_f32 v[68:69], v[60:61], v[52:53], v[68:69] op_sel:[0,1,0]
	v_pk_fma_f32 v[70:71], v[60:61], v[54:55], v[70:71] op_sel_hi:[1,0,1]
	v_pk_fma_f32 v[72:73], v[60:61], v[54:55], v[72:73] op_sel:[0,1,0]
	v_pk_fma_f32 v[0:1], v[0:1], v[48:49], v[66:67] op_sel_hi:[1,0,1]
	v_pk_fma_f32 v[2:3], v[2:3], v[48:49], v[68:69] op_sel:[0,1,0]
	v_pk_fma_f32 v[4:5], v[4:5], v[50:51], v[70:71] op_sel_hi:[1,0,1]
	v_pk_fma_f32 v[6:7], v[6:7], v[50:51], v[72:73] op_sel:[0,1,0]
	ds_write_b32 v84, v64 offset:3456
	ds_write_b32 v84, v76 offset:15744
	s_waitcnt lgkmcnt(7)
	v_pk_mul_f32 v[8:9], v[0:1], v[12:13] op_sel_hi:[1,0]
	v_pk_mul_f32 v[10:11], v[0:1], v[16:17] op_sel_hi:[1,0]
	ds_read_b128 v[40:43], v80 offset:45312
	v_pk_fma_f32 v[8:9], v[2:3], v[12:13], v[8:9] op_sel:[0,1,0]
	v_pk_fma_f32 v[10:11], v[2:3], v[16:17], v[10:11] op_sel:[0,1,0]
	ds_read_b128 v[44:47], v80 offset:44544
	v_pk_fma_f32 v[8:9], v[4:5], v[14:15], v[8:9] op_sel_hi:[1,0,1]
	v_pk_fma_f32 v[10:11], v[4:5], v[18:19], v[10:11] op_sel_hi:[1,0,1]
	ds_read_b128 v[48:51], v80 offset:44800
	v_pk_fma_f32 v[8:9], v[6:7], v[14:15], v[8:9] op_sel:[0,1,0]
	v_pk_fma_f32 v[10:11], v[6:7], v[18:19], v[10:11] op_sel:[0,1,0]
	ds_read_b128 v[52:55], v80 offset:45056
	v_add_f32_dpp v74, v9, v8 row_ror:8 row_mask:0xf bank_mask:0xf bound_ctrl:1
	v_add_f32_dpp v75, v11, v10 row_ror:8 row_mask:0xf bank_mask:0xf bound_ctrl:1
	ds_read_b128 v[56:59], v80 offset:45568
	v_add_f32_dpp v74, v74, v74 quad_perm:[1,0,3,2] row_mask:0xf bank_mask:0xf bound_ctrl:1
	v_add_f32_dpp v75, v75, v75 quad_perm:[1,0,3,2] row_mask:0xf bank_mask:0xf bound_ctrl:1
	ds_read_b32 v60, v81 offset:45824
	v_add_f32_dpp v74, v74, v74 quad_perm:[2,3,0,1] row_mask:0xf bank_mask:0xf bound_ctrl:1
	v_add_f32_dpp v75, v75, v75 quad_perm:[2,3,0,1] row_mask:0xf bank_mask:0xf bound_ctrl:1
	ds_read_b32 v61, v82 offset:45824
	v_add_f32_dpp v76, v74, v74 row_half_mirror row_mask:0xf bank_mask:0xf bound_ctrl:1
	v_add_f32_dpp v36, v75, v75 row_half_mirror row_mask:0xf bank_mask:0xf bound_ctrl:1
	s_nop 0
	v_mov_b32_dpp v77, v76 row_ror:8 row_mask:0xf bank_mask:0xf bound_ctrl:1
	s_waitcnt lgkmcnt(9)
	v_pk_mul_f32 v[66:67], v[76:77], v[28:29] op_sel_hi:[1,0]
	v_pk_mul_f32 v[68:69], v[76:77], v[28:29] op_sel:[0,1]
	v_pk_mul_f32 v[70:71], v[76:77], v[30:31] op_sel_hi:[1,0]
	v_pk_mul_f32 v[72:73], v[76:77], v[30:31] op_sel:[0,1]
	v_pk_fma_f32 v[66:67], v[32:33], v[24:25], v[66:67] op_sel_hi:[1,0,1]
	v_pk_fma_f32 v[68:69], v[32:33], v[24:25], v[68:69] op_sel:[0,1,0]
	v_pk_fma_f32 v[70:71], v[32:33], v[26:27], v[70:71] op_sel_hi:[1,0,1]
	v_pk_fma_f32 v[72:73], v[32:33], v[26:27], v[72:73] op_sel:[0,1,0]
	v_pk_fma_f32 v[0:1], v[0:1], v[20:21], v[66:67] op_sel_hi:[1,0,1]
	v_pk_fma_f32 v[2:3], v[2:3], v[20:21], v[68:69] op_sel:[0,1,0]
	v_pk_fma_f32 v[4:5], v[4:5], v[22:23], v[70:71] op_sel_hi:[1,0,1]
	v_pk_fma_f32 v[6:7], v[6:7], v[22:23], v[72:73] op_sel:[0,1,0]
	ds_write_b32 v84, v36 offset:3584
	ds_write_b32 v84, v76 offset:15872
	s_waitcnt lgkmcnt(7)
	v_pk_mul_f32 v[8:9], v[0:1], v[40:41] op_sel_hi:[1,0]
	v_pk_mul_f32 v[10:11], v[0:1], v[44:45] op_sel_hi:[1,0]
	ds_read_b128 v[12:15], v80 offset:46848
	v_pk_fma_f32 v[8:9], v[2:3], v[40:41], v[8:9] op_sel:[0,1,0]
	v_pk_fma_f32 v[10:11], v[2:3], v[44:45], v[10:11] op_sel:[0,1,0]
	ds_read_b128 v[16:19], v80 offset:46080
	v_pk_fma_f32 v[8:9], v[4:5], v[42:43], v[8:9] op_sel_hi:[1,0,1]
	v_pk_fma_f32 v[10:11], v[4:5], v[46:47], v[10:11] op_sel_hi:[1,0,1]
	ds_read_b128 v[20:23], v80 offset:46336
	v_pk_fma_f32 v[8:9], v[6:7], v[42:43], v[8:9] op_sel:[0,1,0]
	v_pk_fma_f32 v[10:11], v[6:7], v[46:47], v[10:11] op_sel:[0,1,0]
	ds_read_b128 v[24:27], v80 offset:46592
	v_add_f32_dpp v74, v9, v8 row_ror:8 row_mask:0xf bank_mask:0xf bound_ctrl:1
	v_add_f32_dpp v75, v11, v10 row_ror:8 row_mask:0xf bank_mask:0xf bound_ctrl:1
	ds_read_b128 v[28:31], v80 offset:47104
	v_add_f32_dpp v74, v74, v74 quad_perm:[1,0,3,2] row_mask:0xf bank_mask:0xf bound_ctrl:1
	v_add_f32_dpp v75, v75, v75 quad_perm:[1,0,3,2] row_mask:0xf bank_mask:0xf bound_ctrl:1
	ds_read_b32 v32, v81 offset:47360
	v_add_f32_dpp v74, v74, v74 quad_perm:[2,3,0,1] row_mask:0xf bank_mask:0xf bound_ctrl:1
	v_add_f32_dpp v75, v75, v75 quad_perm:[2,3,0,1] row_mask:0xf bank_mask:0xf bound_ctrl:1
	ds_read_b32 v33, v82 offset:47360
	v_add_f32_dpp v76, v74, v74 row_half_mirror row_mask:0xf bank_mask:0xf bound_ctrl:1
	v_add_f32_dpp v64, v75, v75 row_half_mirror row_mask:0xf bank_mask:0xf bound_ctrl:1
	s_nop 0
	v_mov_b32_dpp v77, v76 row_ror:8 row_mask:0xf bank_mask:0xf bound_ctrl:1
	s_waitcnt lgkmcnt(9)
	v_pk_mul_f32 v[66:67], v[76:77], v[56:57] op_sel_hi:[1,0]
	v_pk_mul_f32 v[68:69], v[76:77], v[56:57] op_sel:[0,1]
	v_pk_mul_f32 v[70:71], v[76:77], v[58:59] op_sel_hi:[1,0]
	v_pk_mul_f32 v[72:73], v[76:77], v[58:59] op_sel:[0,1]
	v_pk_fma_f32 v[66:67], v[60:61], v[52:53], v[66:67] op_sel_hi:[1,0,1]
	v_pk_fma_f32 v[68:69], v[60:61], v[52:53], v[68:69] op_sel:[0,1,0]
	v_pk_fma_f32 v[70:71], v[60:61], v[54:55], v[70:71] op_sel_hi:[1,0,1]
	v_pk_fma_f32 v[72:73], v[60:61], v[54:55], v[72:73] op_sel:[0,1,0]
	v_pk_fma_f32 v[0:1], v[0:1], v[48:49], v[66:67] op_sel_hi:[1,0,1]
	v_pk_fma_f32 v[2:3], v[2:3], v[48:49], v[68:69] op_sel:[0,1,0]
	v_pk_fma_f32 v[4:5], v[4:5], v[50:51], v[70:71] op_sel_hi:[1,0,1]
	v_pk_fma_f32 v[6:7], v[6:7], v[50:51], v[72:73] op_sel:[0,1,0]
	ds_write_b32 v84, v64 offset:3712
	ds_write_b32 v84, v76 offset:16000
	s_waitcnt lgkmcnt(7)
	v_pk_mul_f32 v[8:9], v[0:1], v[12:13] op_sel_hi:[1,0]
	v_pk_mul_f32 v[10:11], v[0:1], v[16:17] op_sel_hi:[1,0]
	ds_read_b128 v[40:43], v80 offset:48384
	v_pk_fma_f32 v[8:9], v[2:3], v[12:13], v[8:9] op_sel:[0,1,0]
	v_pk_fma_f32 v[10:11], v[2:3], v[16:17], v[10:11] op_sel:[0,1,0]
	ds_read_b128 v[44:47], v80 offset:47616
	v_pk_fma_f32 v[8:9], v[4:5], v[14:15], v[8:9] op_sel_hi:[1,0,1]
	v_pk_fma_f32 v[10:11], v[4:5], v[18:19], v[10:11] op_sel_hi:[1,0,1]
	ds_read_b128 v[48:51], v80 offset:47872
	v_pk_fma_f32 v[8:9], v[6:7], v[14:15], v[8:9] op_sel:[0,1,0]
	v_pk_fma_f32 v[10:11], v[6:7], v[18:19], v[10:11] op_sel:[0,1,0]
	ds_read_b128 v[52:55], v80 offset:48128
	v_add_f32_dpp v74, v9, v8 row_ror:8 row_mask:0xf bank_mask:0xf bound_ctrl:1
	v_add_f32_dpp v75, v11, v10 row_ror:8 row_mask:0xf bank_mask:0xf bound_ctrl:1
	ds_read_b128 v[56:59], v80 offset:48640
	v_add_f32_dpp v74, v74, v74 quad_perm:[1,0,3,2] row_mask:0xf bank_mask:0xf bound_ctrl:1
	v_add_f32_dpp v75, v75, v75 quad_perm:[1,0,3,2] row_mask:0xf bank_mask:0xf bound_ctrl:1
	ds_read_b32 v60, v81 offset:48896
	v_add_f32_dpp v74, v74, v74 quad_perm:[2,3,0,1] row_mask:0xf bank_mask:0xf bound_ctrl:1
	v_add_f32_dpp v75, v75, v75 quad_perm:[2,3,0,1] row_mask:0xf bank_mask:0xf bound_ctrl:1
	ds_read_b32 v61, v82 offset:48896
	v_add_f32_dpp v76, v74, v74 row_half_mirror row_mask:0xf bank_mask:0xf bound_ctrl:1
	v_add_f32_dpp v36, v75, v75 row_half_mirror row_mask:0xf bank_mask:0xf bound_ctrl:1
	s_nop 0
	v_mov_b32_dpp v77, v76 row_ror:8 row_mask:0xf bank_mask:0xf bound_ctrl:1
	s_waitcnt lgkmcnt(9)
	v_pk_mul_f32 v[66:67], v[76:77], v[28:29] op_sel_hi:[1,0]
	v_pk_mul_f32 v[68:69], v[76:77], v[28:29] op_sel:[0,1]
	v_pk_mul_f32 v[70:71], v[76:77], v[30:31] op_sel_hi:[1,0]
	v_pk_mul_f32 v[72:73], v[76:77], v[30:31] op_sel:[0,1]
	v_pk_fma_f32 v[66:67], v[32:33], v[24:25], v[66:67] op_sel_hi:[1,0,1]
	v_pk_fma_f32 v[68:69], v[32:33], v[24:25], v[68:69] op_sel:[0,1,0]
	v_pk_fma_f32 v[70:71], v[32:33], v[26:27], v[70:71] op_sel_hi:[1,0,1]
	v_pk_fma_f32 v[72:73], v[32:33], v[26:27], v[72:73] op_sel:[0,1,0]
	v_pk_fma_f32 v[0:1], v[0:1], v[20:21], v[66:67] op_sel_hi:[1,0,1]
	v_pk_fma_f32 v[2:3], v[2:3], v[20:21], v[68:69] op_sel:[0,1,0]
	v_pk_fma_f32 v[4:5], v[4:5], v[22:23], v[70:71] op_sel_hi:[1,0,1]
	v_pk_fma_f32 v[6:7], v[6:7], v[22:23], v[72:73] op_sel:[0,1,0]
	ds_write_b32 v84, v36 offset:3840
	ds_write_b32 v84, v76 offset:16128
	s_waitcnt lgkmcnt(7)
	v_pk_mul_f32 v[8:9], v[0:1], v[40:41] op_sel_hi:[1,0]
	v_pk_mul_f32 v[10:11], v[0:1], v[44:45] op_sel_hi:[1,0]
	v_pk_fma_f32 v[8:9], v[2:3], v[40:41], v[8:9] op_sel:[0,1,0]
	v_pk_fma_f32 v[10:11], v[2:3], v[44:45], v[10:11] op_sel:[0,1,0]
	v_pk_fma_f32 v[8:9], v[4:5], v[42:43], v[8:9] op_sel_hi:[1,0,1]
	v_pk_fma_f32 v[10:11], v[4:5], v[46:47], v[10:11] op_sel_hi:[1,0,1]
	v_pk_fma_f32 v[8:9], v[6:7], v[42:43], v[8:9] op_sel:[0,1,0]
	v_pk_fma_f32 v[10:11], v[6:7], v[46:47], v[10:11] op_sel:[0,1,0]
	s_nop 0
	v_add_f32_dpp v74, v9, v8 row_ror:8 row_mask:0xf bank_mask:0xf bound_ctrl:1
	v_add_f32_dpp v75, v11, v10 row_ror:8 row_mask:0xf bank_mask:0xf bound_ctrl:1
	s_nop 0
	v_add_f32_dpp v74, v74, v74 quad_perm:[1,0,3,2] row_mask:0xf bank_mask:0xf bound_ctrl:1
	v_add_f32_dpp v75, v75, v75 quad_perm:[1,0,3,2] row_mask:0xf bank_mask:0xf bound_ctrl:1
	s_nop 0
	v_add_f32_dpp v74, v74, v74 quad_perm:[2,3,0,1] row_mask:0xf bank_mask:0xf bound_ctrl:1
	v_add_f32_dpp v75, v75, v75 quad_perm:[2,3,0,1] row_mask:0xf bank_mask:0xf bound_ctrl:1
	s_nop 0
	v_add_f32_dpp v76, v74, v74 row_half_mirror row_mask:0xf bank_mask:0xf bound_ctrl:1
	v_add_f32_dpp v64, v75, v75 row_half_mirror row_mask:0xf bank_mask:0xf bound_ctrl:1
	s_nop 0
	v_mov_b32_dpp v77, v76 row_ror:8 row_mask:0xf bank_mask:0xf bound_ctrl:1
	s_waitcnt lgkmcnt(2)
	v_pk_mul_f32 v[66:67], v[76:77], v[56:57] op_sel_hi:[1,0]
	v_pk_mul_f32 v[68:69], v[76:77], v[56:57] op_sel:[0,1]
	v_pk_mul_f32 v[70:71], v[76:77], v[58:59] op_sel_hi:[1,0]
	v_pk_mul_f32 v[72:73], v[76:77], v[58:59] op_sel:[0,1]
	v_pk_fma_f32 v[66:67], v[60:61], v[52:53], v[66:67] op_sel_hi:[1,0,1]
	v_pk_fma_f32 v[68:69], v[60:61], v[52:53], v[68:69] op_sel:[0,1,0]
	v_pk_fma_f32 v[70:71], v[60:61], v[54:55], v[70:71] op_sel_hi:[1,0,1]
	v_pk_fma_f32 v[72:73], v[60:61], v[54:55], v[72:73] op_sel:[0,1,0]
	v_pk_fma_f32 v[0:1], v[0:1], v[48:49], v[66:67] op_sel_hi:[1,0,1]
	v_pk_fma_f32 v[2:3], v[2:3], v[48:49], v[68:69] op_sel:[0,1,0]
	v_pk_fma_f32 v[4:5], v[4:5], v[50:51], v[70:71] op_sel_hi:[1,0,1]
	v_pk_fma_f32 v[6:7], v[6:7], v[50:51], v[72:73] op_sel:[0,1,0]
	ds_write_b32 v84, v64 offset:3968
	ds_write_b32 v84, v76 offset:16256
